# v15 with the m0 write placed before the address add at 15 LDS-DMA sites (wait state restored), no other change
# speedup vs baseline: 1.0114x; 1.0114x over previous
; #define PG8_STAGE(bufoff, gbase, voff) do { _Pragma("unroll") for (int _i = 0; _i < 2; ++_i) \
;         __builtin_amdgcn_global_load_lds((const unsigned*)((const char*)(gbase) + (voff)[_i]), (PG8_LAS unsigned*)(lds + (bufoff) + ldsw + _i * 8192), 16, 0, 0); } while (0)
; #define PG8_LDA(dst, b, h) do { _Pragma("unroll") for (int m = 0; m < 4; ++m) _Pragma("unroll") for (int k = 0; k < 2; ++k) dst[m][k] = *(const PG8_LAS bf16x8*)(lds + PG8_SA(b, h) + aoff + m * 2048 + k * 1024); } while (0)
; #define PG8_LDB(dst, b, h) do { _Pragma("unroll") for (int n = 0; n < 2; ++n) _Pragma("unroll") for (int k = 0; k < 2; ++k) dst[n][k] = *(const PG8_LAS bf16x8*)(lds + PG8_SB(b, h) + boff + n * 2048 + k * 1024); } while (0)
; #define PG8_MMA(ai, bj, At, Bt) do { __builtin_amdgcn_s_setprio(1); _Pragma("unroll") for (int m = 0; m < 4; ++m) _Pragma("unroll") for (int n = 0; n < 2; ++n) _Pragma("unroll") for (int k = 0; k < 2; ++k) \
;         acc[ai][bj][m][n] = __builtin_amdgcn_mfma_f32_16x16x32_bf16(Bt[n][k], At[m][k], acc[ai][bj][m][n], 0, 0, 0); __builtin_amdgcn_s_setprio(0); } while (0)
; #define PG8_WAIT_V(n) asm volatile("s_waitcnt vmcnt(" #n ")" ::: "memory")
; #define PG8_BAR __builtin_amdgcn_s_barrier()
; template <class Epi, class Sched, bool ALIGN_EPI = false, bool SP2 = false>
; __device__ __forceinline__ void gemm_phase(PG8_LAS unsigned char* lds, const Gemm g, const Sched& S, const Epi& E) {
;     ...
;         for (int t = 0; t < nt; t += 2) {
;             const bool last = (t == nt - 2);
;             const char* a1 = cA + (size_t)(t + 1) * kstep;
;             const char* a2 = last ? nA : cA + (size_t)(t + 2) * kstep; const char* b2 = last ? nB : cB + (size_t)(t + 2) * kstep;
;             const char* a3 = a2 + kstep; const char* b3 = b2 + kstep;
;             if (last && has_next) S.a_ready(nxt);
;             if constexpr (SP2) {
;             PG8_LDB(B0, 0, 0); PG8_LDB(B1, 0, 1); PG8_SCHED; PG8_LDA(At, 0, 0); PG8_STAGE(PG8_SA(1, 1), a1 + hstepA, voffA);
;             PG8_WAIT_V(8); PG8_WAIT_L(0); PG8_BAR; PG8_MMA(0, 0, At, B0); PG8_MMA(0, 1, At, B1); PG8_BAR; PG8_SCHED;
;             PG8_LDA(At, 0, 1); PG8_STAGE(PG8_SB(0, 0), b2, voffB); PG8_STAGE(PG8_SB(0, 1), b2 + hstepB, voffB); PG8_STAGE(PG8_SA(0, 0), a2, voffA);
;             PG8_WAIT_V(8); PG8_WAIT_L(0); PG8_BAR; PG8_MMA(1, 0, At, B0); PG8_MMA(1, 1, At, B1); PG8_BAR; PG8_SCHED;
.LBB0_171:
	v_add_u32_e32 v76, 0x10000, v162
	v_add_u32_e32 v158, 0x14000, v162
	ds_read_b128 v[64:67], v76
	ds_read_b128 v[68:71], v76 offset:1024
	ds_read_b128 v[72:75], v76 offset:2048
	ds_read_b128 v[76:79], v76 offset:3072
	ds_read_b128 v[154:157], v158
	ds_read_b128 v[164:167], v158 offset:1024
	ds_read_b128 v[168:171], v158 offset:2048
	ds_read_b128 v[172:175], v158 offset:3072
	ds_read_b128 v[176:179], v163
	ds_read_b128 v[180:183], v163 offset:1024
	ds_read_b128 v[184:187], v163 offset:2048
	ds_read_b128 v[194:197], v163 offset:3072
	ds_read_b128 v[230:233], v163 offset:4096
	ds_read_b128 v[234:237], v163 offset:5120
	ds_read_b128 v[238:241], v163 offset:6144
	ds_read_b128 v[242:245], v163 offset:7168
	s_add_u32 s50, s8, 0xfffc0080
	s_addc_u32 s51, s9, -1
	s_add_i32 s60, 0, 0x10000
	s_cmp_eq_u32 s59, 12
	s_cselect_b32 s53, s11, s51
	s_cselect_b32 s52, s37, s50
	s_cselect_b32 s51, s35, s58
	s_cselect_b32 s50, s54, s55
	s_add_i32 s62, 0, 0x14000
	s_add_i32 m0, s57, 0xc000
	v_lshl_add_u64 v[158:159], s[8:9], 0, v[150:151]
	global_load_lds_dwordx4 v[158:159], off
	s_add_i32 m0, s57, 0xe000
	v_lshl_add_u64 v[158:159], s[8:9], 0, v[152:153]
	global_load_lds_dwordx4 v[158:159], off
	s_waitcnt vmcnt(8)
	s_waitcnt lgkmcnt(0)
	s_barrier
	s_setprio 1
	s_waitcnt lgkmcnt(0)
	v_mfma_f32_16x16x32_bf16 v[140:143], v[64:67], v[176:179], v[140:143]
	v_mfma_f32_16x16x32_bf16 v[136:139], v[72:75], v[176:179], v[136:139]
	v_mfma_f32_16x16x32_bf16 v[124:127], v[64:67], v[184:187], v[124:127]
	v_mfma_f32_16x16x32_bf16 v[120:123], v[72:75], v[184:187], v[120:123]
	v_mfma_f32_16x16x32_bf16 v[108:111], v[64:67], v[230:233], v[108:111]
	v_mfma_f32_16x16x32_bf16 v[104:107], v[72:75], v[230:233], v[104:107]
	v_mfma_f32_16x16x32_bf16 v[92:95], v[64:67], v[238:241], v[92:95]
	v_mfma_f32_16x16x32_bf16 v[88:91], v[72:75], v[238:241], v[88:91]
	v_mfma_f32_16x16x32_bf16 v[140:143], v[68:71], v[180:183], v[140:143]
	v_mfma_f32_16x16x32_bf16 v[136:139], v[76:79], v[180:183], v[136:139]
	v_mfma_f32_16x16x32_bf16 v[124:127], v[68:71], v[194:197], v[124:127]
	v_mfma_f32_16x16x32_bf16 v[120:123], v[76:79], v[194:197], v[120:123]
	v_mfma_f32_16x16x32_bf16 v[108:111], v[68:71], v[234:237], v[108:111]
	v_mfma_f32_16x16x32_bf16 v[104:107], v[76:79], v[234:237], v[104:107]
	v_mfma_f32_16x16x32_bf16 v[92:95], v[68:71], v[242:245], v[92:95]
	v_mfma_f32_16x16x32_bf16 v[88:91], v[76:79], v[242:245], v[88:91]
	s_setprio 0
	s_setprio 1
	v_mfma_f32_16x16x32_bf16 v[132:135], v[154:157], v[176:179], v[132:135]
	v_mfma_f32_16x16x32_bf16 v[128:131], v[168:171], v[176:179], v[128:131]
	v_mfma_f32_16x16x32_bf16 v[116:119], v[154:157], v[184:187], v[116:119]
	v_mfma_f32_16x16x32_bf16 v[112:115], v[168:171], v[184:187], v[112:115]
	v_mfma_f32_16x16x32_bf16 v[100:103], v[154:157], v[230:233], v[100:103]
	v_mfma_f32_16x16x32_bf16 v[96:99], v[168:171], v[230:233], v[96:99]
	v_mfma_f32_16x16x32_bf16 v[84:87], v[154:157], v[238:241], v[84:87]
	v_mfma_f32_16x16x32_bf16 v[80:83], v[168:171], v[238:241], v[80:83]
	v_mfma_f32_16x16x32_bf16 v[132:135], v[164:167], v[180:183], v[132:135]
	v_mfma_f32_16x16x32_bf16 v[128:131], v[172:175], v[180:183], v[128:131]
	v_mfma_f32_16x16x32_bf16 v[116:119], v[164:167], v[194:197], v[116:119]
	v_mfma_f32_16x16x32_bf16 v[112:115], v[172:175], v[194:197], v[112:115]
	v_mfma_f32_16x16x32_bf16 v[100:103], v[164:167], v[234:237], v[100:103]
	v_mfma_f32_16x16x32_bf16 v[96:99], v[172:175], v[234:237], v[96:99]
	v_mfma_f32_16x16x32_bf16 v[84:87], v[164:167], v[242:245], v[84:87]
	v_mfma_f32_16x16x32_bf16 v[80:83], v[172:175], v[242:245], v[80:83]
	s_setprio 0
	s_barrier
	ds_read_b128 v[176:179], v163 offset:16384
	ds_read_b128 v[180:183], v163 offset:17408
	ds_read_b128 v[184:187], v163 offset:18432
	ds_read_b128 v[194:197], v163 offset:19456
	ds_read_b128 v[230:233], v163 offset:20480
	ds_read_b128 v[234:237], v163 offset:21504
	ds_read_b128 v[238:241], v163 offset:22528
	ds_read_b128 v[242:245], v163 offset:23552
	s_add_i32 s60, s60, s69
	s_mov_b32 m0, s60
	v_lshl_add_u64 v[158:159], s[50:51], 0, v[188:189]
	global_load_lds_dwordx4 v[158:159], off
	s_add_i32 m0, s60, 0x2000
	s_add_u32 s60, s50, 0x40000
	v_lshl_add_u64 v[246:247], s[50:51], 0, v[148:149]
	s_addc_u32 s61, s51, 0
	s_add_i32 s62, s62, s69
	global_load_lds_dwordx4 v[246:247], off
	v_lshl_add_u64 v[248:249], s[60:61], 0, v[188:189]
	s_mov_b32 m0, s62
	v_lshl_add_u64 v[250:251], s[52:53], 0, v[146:147]
	global_load_lds_dwordx4 v[248:249], off
	s_add_i32 m0, s62, 0x2000
	v_lshl_add_u64 v[248:249], s[60:61], 0, v[148:149]
	global_load_lds_dwordx4 v[248:249], off
	s_mov_b32 m0, s57
	v_lshl_add_u64 v[248:249], s[52:53], 0, v[144:145]
	global_load_lds_dwordx4 v[248:249], off
	s_mov_b32 m0, s78
	s_nop 0
	global_load_lds_dwordx4 v[250:251], off
	s_waitcnt vmcnt(8)
	s_waitcnt lgkmcnt(0)
	s_barrier
; #define PG8_STAGE(bufoff, gbase, voff) do { _Pragma("unroll") for (int _i = 0; _i < 2; ++_i) \
;         __builtin_amdgcn_global_load_lds((const unsigned*)((const char*)(gbase) + (voff)[_i]), (PG8_LAS unsigned*)(lds + (bufoff) + ldsw + _i * 8192), 16, 0, 0); } while (0)
; #define PG8_LDA(dst, b, h) do { _Pragma("unroll") for (int m = 0; m < 4; ++m) _Pragma("unroll") for (int k = 0; k < 2; ++k) dst[m][k] = *(const PG8_LAS bf16x8*)(lds + PG8_SA(b, h) + aoff + m * 2048 + k * 1024); } while (0)
; #define PG8_LDB(dst, b, h) do { _Pragma("unroll") for (int n = 0; n < 2; ++n) _Pragma("unroll") for (int k = 0; k < 2; ++k) dst[n][k] = *(const PG8_LAS bf16x8*)(lds + PG8_SB(b, h) + boff + n * 2048 + k * 1024); } while (0)
; #define PG8_MMA(ai, bj, At, Bt) do { __builtin_amdgcn_s_setprio(1); _Pragma("unroll") for (int m = 0; m < 4; ++m) _Pragma("unroll") for (int n = 0; n < 2; ++n) _Pragma("unroll") for (int k = 0; k < 2; ++k) \
;         acc[ai][bj][m][n] = __builtin_amdgcn_mfma_f32_16x16x32_bf16(Bt[n][k], At[m][k], acc[ai][bj][m][n], 0, 0, 0); __builtin_amdgcn_s_setprio(0); } while (0)
; #define PG8_WAIT_V(n) asm volatile("s_waitcnt vmcnt(" #n ")" ::: "memory")
; #define PG8_WAIT_L(n) asm volatile("s_waitcnt lgkmcnt(" #n ")" ::: "memory")
; #define PG8_BAR __builtin_amdgcn_s_barrier()
; #define PG8_SCHED __builtin_amdgcn_sched_barrier(0)
; template <class Epi, class Sched, bool ALIGN_EPI = false, bool SP2 = false>
; __device__ __forceinline__ void gemm_phase(PG8_LAS unsigned char* lds, const Gemm g, const Sched& S, const Epi& E) {
;     ...
;             PG8_WAIT_V(8); PG8_WAIT_L(0); PG8_BAR; PG8_MMA(1, 0, At, B0); PG8_MMA(1, 1, At, B1); PG8_BAR; PG8_SCHED;
;             PG8_LDB(B0, 1, 0); PG8_LDB(B1, 1, 1); PG8_SCHED; PG8_LDA(At, 1, 0); PG8_STAGE(PG8_SA(0, 1), a2 + hstepA, voffA);
;             PG8_WAIT_V(8); PG8_WAIT_L(0); PG8_BAR; PG8_MMA(0, 0, At, B0); PG8_MMA(0, 1, At, B1); PG8_BAR; PG8_SCHED;
	s_setprio 1
	s_waitcnt lgkmcnt(0)
	v_mfma_f32_16x16x32_bf16 v[60:63], v[64:67], v[176:179], v[60:63]
	v_mfma_f32_16x16x32_bf16 v[56:59], v[72:75], v[176:179], v[56:59]
	v_mfma_f32_16x16x32_bf16 v[44:47], v[64:67], v[184:187], v[44:47]
	v_mfma_f32_16x16x32_bf16 v[40:43], v[72:75], v[184:187], v[40:43]
	v_mfma_f32_16x16x32_bf16 v[28:31], v[64:67], v[230:233], v[28:31]
	v_mfma_f32_16x16x32_bf16 v[24:27], v[72:75], v[230:233], v[24:27]
	v_mfma_f32_16x16x32_bf16 v[12:15], v[64:67], v[238:241], v[12:15]
	v_mfma_f32_16x16x32_bf16 v[8:11], v[72:75], v[238:241], v[8:11]
	v_mfma_f32_16x16x32_bf16 v[60:63], v[68:71], v[180:183], v[60:63]
	v_mfma_f32_16x16x32_bf16 v[56:59], v[76:79], v[180:183], v[56:59]
	v_mfma_f32_16x16x32_bf16 v[44:47], v[68:71], v[194:197], v[44:47]
	v_mfma_f32_16x16x32_bf16 v[40:43], v[76:79], v[194:197], v[40:43]
	v_mfma_f32_16x16x32_bf16 v[28:31], v[68:71], v[234:237], v[28:31]
	v_mfma_f32_16x16x32_bf16 v[24:27], v[76:79], v[234:237], v[24:27]
	v_mfma_f32_16x16x32_bf16 v[12:15], v[68:71], v[242:245], v[12:15]
	v_mfma_f32_16x16x32_bf16 v[8:11], v[76:79], v[242:245], v[8:11]
	s_setprio 0
	s_setprio 1
	v_mfma_f32_16x16x32_bf16 v[52:55], v[154:157], v[176:179], v[52:55]
	v_mfma_f32_16x16x32_bf16 v[48:51], v[168:171], v[176:179], v[48:51]
	v_mfma_f32_16x16x32_bf16 v[36:39], v[154:157], v[184:187], v[36:39]
	v_mfma_f32_16x16x32_bf16 v[32:35], v[168:171], v[184:187], v[32:35]
	v_mfma_f32_16x16x32_bf16 v[20:23], v[154:157], v[230:233], v[20:23]
	v_mfma_f32_16x16x32_bf16 v[16:19], v[168:171], v[230:233], v[16:19]
	v_mfma_f32_16x16x32_bf16 v[4:7], v[154:157], v[238:241], v[4:7]
	v_mfma_f32_16x16x32_bf16 v[0:3], v[168:171], v[238:241], v[0:3]
	v_mfma_f32_16x16x32_bf16 v[52:55], v[164:167], v[180:183], v[52:55]
	v_mfma_f32_16x16x32_bf16 v[48:51], v[172:175], v[180:183], v[48:51]
	v_mfma_f32_16x16x32_bf16 v[36:39], v[164:167], v[194:197], v[36:39]
	v_mfma_f32_16x16x32_bf16 v[32:35], v[172:175], v[194:197], v[32:35]
	v_mfma_f32_16x16x32_bf16 v[20:23], v[164:167], v[234:237], v[20:23]
	v_mfma_f32_16x16x32_bf16 v[16:19], v[172:175], v[234:237], v[16:19]
	v_mfma_f32_16x16x32_bf16 v[4:7], v[164:167], v[242:245], v[4:7]
	v_mfma_f32_16x16x32_bf16 v[0:3], v[172:175], v[242:245], v[0:3]
	s_setprio 0
	s_barrier
	v_add_u32_e32 v76, 0x18000, v162
	v_add_u32_e32 v172, 0x1c000, v162
	ds_read_b128 v[64:67], v76
	ds_read_b128 v[68:71], v76 offset:1024
	ds_read_b128 v[72:75], v76 offset:2048
	ds_read_b128 v[76:79], v76 offset:3072
	ds_read_b128 v[154:157], v172
	ds_read_b128 v[164:167], v172 offset:1024
	ds_read_b128 v[168:171], v172 offset:2048
	ds_read_b128 v[172:175], v172 offset:3072
	ds_read_b128 v[176:179], v163 offset:32768
	ds_read_b128 v[180:183], v163 offset:33792
	ds_read_b128 v[184:187], v163 offset:34816
	ds_read_b128 v[194:197], v163 offset:35840
	ds_read_b128 v[230:233], v163 offset:36864
	ds_read_b128 v[234:237], v163 offset:37888
	ds_read_b128 v[238:241], v163 offset:38912
	ds_read_b128 v[242:245], v163 offset:39936
	s_add_i32 s60, 0, 0x18000
	s_add_i32 s61, 0, 0x1c000
	s_add_u32 s52, s52, 0x40000
	s_addc_u32 s53, s53, 0
	s_mov_b32 m0, s81
	v_lshl_add_u64 v[252:253], s[52:53], 0, v[144:145]
	global_load_lds_dwordx4 v[252:253], off
	s_mov_b32 m0, s80
	v_lshl_add_u64 v[252:253], s[52:53], 0, v[146:147]
	global_load_lds_dwordx4 v[252:253], off
	s_waitcnt vmcnt(8)
	s_waitcnt lgkmcnt(0)
	s_barrier
	s_setprio 1
	s_waitcnt lgkmcnt(0)
	v_mfma_f32_16x16x32_bf16 v[140:143], v[64:67], v[176:179], v[140:143]
	v_mfma_f32_16x16x32_bf16 v[136:139], v[72:75], v[176:179], v[136:139]
	v_mfma_f32_16x16x32_bf16 v[124:127], v[64:67], v[184:187], v[124:127]
	v_mfma_f32_16x16x32_bf16 v[120:123], v[72:75], v[184:187], v[120:123]
	v_mfma_f32_16x16x32_bf16 v[108:111], v[64:67], v[230:233], v[108:111]
	v_mfma_f32_16x16x32_bf16 v[104:107], v[72:75], v[230:233], v[104:107]
	v_mfma_f32_16x16x32_bf16 v[92:95], v[64:67], v[238:241], v[92:95]
	v_mfma_f32_16x16x32_bf16 v[88:91], v[72:75], v[238:241], v[88:91]
	v_mfma_f32_16x16x32_bf16 v[140:143], v[68:71], v[180:183], v[140:143]
	v_mfma_f32_16x16x32_bf16 v[136:139], v[76:79], v[180:183], v[136:139]
	v_mfma_f32_16x16x32_bf16 v[124:127], v[68:71], v[194:197], v[124:127]
	v_mfma_f32_16x16x32_bf16 v[120:123], v[76:79], v[194:197], v[120:123]
	v_mfma_f32_16x16x32_bf16 v[108:111], v[68:71], v[234:237], v[108:111]
	v_mfma_f32_16x16x32_bf16 v[104:107], v[76:79], v[234:237], v[104:107]
	v_mfma_f32_16x16x32_bf16 v[92:95], v[68:71], v[242:245], v[92:95]
	v_mfma_f32_16x16x32_bf16 v[88:91], v[76:79], v[242:245], v[88:91]
	s_setprio 0
	s_setprio 1
	v_mfma_f32_16x16x32_bf16 v[132:135], v[154:157], v[176:179], v[132:135]
	v_mfma_f32_16x16x32_bf16 v[128:131], v[168:171], v[176:179], v[128:131]
	v_mfma_f32_16x16x32_bf16 v[116:119], v[154:157], v[184:187], v[116:119]
	v_mfma_f32_16x16x32_bf16 v[112:115], v[168:171], v[184:187], v[112:115]
	v_mfma_f32_16x16x32_bf16 v[100:103], v[154:157], v[230:233], v[100:103]
	v_mfma_f32_16x16x32_bf16 v[96:99], v[168:171], v[230:233], v[96:99]
	v_mfma_f32_16x16x32_bf16 v[84:87], v[154:157], v[238:241], v[84:87]
	v_mfma_f32_16x16x32_bf16 v[80:83], v[168:171], v[238:241], v[80:83]
	v_mfma_f32_16x16x32_bf16 v[132:135], v[164:167], v[180:183], v[132:135]
	v_mfma_f32_16x16x32_bf16 v[128:131], v[172:175], v[180:183], v[128:131]
	v_mfma_f32_16x16x32_bf16 v[116:119], v[164:167], v[194:197], v[116:119]
	v_mfma_f32_16x16x32_bf16 v[112:115], v[172:175], v[194:197], v[112:115]
	v_mfma_f32_16x16x32_bf16 v[100:103], v[164:167], v[234:237], v[100:103]
	v_mfma_f32_16x16x32_bf16 v[96:99], v[172:175], v[234:237], v[96:99]
	v_mfma_f32_16x16x32_bf16 v[84:87], v[164:167], v[242:245], v[84:87]
	v_mfma_f32_16x16x32_bf16 v[80:83], v[172:175], v[242:245], v[80:83]
	s_setprio 0
	s_barrier
; #define PG8_STAGE(bufoff, gbase, voff) do { _Pragma("unroll") for (int _i = 0; _i < 2; ++_i) \
;         __builtin_amdgcn_global_load_lds((const unsigned*)((const char*)(gbase) + (voff)[_i]), (PG8_LAS unsigned*)(lds + (bufoff) + ldsw + _i * 8192), 16, 0, 0); } while (0)
; #define PG8_LDA(dst, b, h) do { _Pragma("unroll") for (int m = 0; m < 4; ++m) _Pragma("unroll") for (int k = 0; k < 2; ++k) dst[m][k] = *(const PG8_LAS bf16x8*)(lds + PG8_SA(b, h) + aoff + m * 2048 + k * 1024); } while (0)
; #define PG8_MMA(ai, bj, At, Bt) do { __builtin_amdgcn_s_setprio(1); _Pragma("unroll") for (int m = 0; m < 4; ++m) _Pragma("unroll") for (int n = 0; n < 2; ++n) _Pragma("unroll") for (int k = 0; k < 2; ++k) \
;         acc[ai][bj][m][n] = __builtin_amdgcn_mfma_f32_16x16x32_bf16(Bt[n][k], At[m][k], acc[ai][bj][m][n], 0, 0, 0); __builtin_amdgcn_s_setprio(0); } while (0)
; #define PG8_WAIT_V(n) asm volatile("s_waitcnt vmcnt(" #n ")" ::: "memory")
; #define PG8_WAIT_L(n) asm volatile("s_waitcnt lgkmcnt(" #n ")" ::: "memory")
; #define PG8_BAR __builtin_amdgcn_s_barrier()
; #define PG8_SCHED __builtin_amdgcn_sched_barrier(0)
; template <class Epi, class Sched, bool ALIGN_EPI = false, bool SP2 = false>
; __device__ __forceinline__ void gemm_phase(PG8_LAS unsigned char* lds, const Gemm g, const Sched& S, const Epi& E) {
;     ...
;         for (int t = 0; t < nt; t += 2) {
;     ...
;             PG8_LDA(At, 1, 1); PG8_STAGE(PG8_SB(1, 0), b3, voffB); PG8_STAGE(PG8_SB(1, 1), b3 + hstepB, voffB); PG8_STAGE(PG8_SA(1, 0), a3, voffA);
;             PG8_WAIT_V(8); PG8_WAIT_L(0); PG8_BAR; PG8_MMA(1, 0, At, B0); PG8_MMA(1, 1, At, B1); PG8_BAR; PG8_SCHED;
	ds_read_b128 v[176:179], v163 offset:49152
	ds_read_b128 v[180:183], v163 offset:50176
	ds_read_b128 v[184:187], v163 offset:51200
	ds_read_b128 v[194:197], v163 offset:52224
	ds_read_b128 v[230:233], v163 offset:53248
	ds_read_b128 v[234:237], v163 offset:54272
	ds_read_b128 v[238:241], v163 offset:55296
	ds_read_b128 v[242:245], v163 offset:56320
	s_add_i32 s52, s60, s69
	s_mov_b32 m0, s52
	v_lshl_add_u64 v[158:159], v[158:159], 0, s[94:95]
	global_load_lds_dwordx4 v[158:159], off
	s_add_i32 m0, s52, 0x2000
	s_add_u32 s50, s50, 0x40080
	v_lshl_add_u64 v[158:159], v[246:247], 0, s[94:95]
	s_addc_u32 s51, s51, 0
	s_add_i32 s52, s61, s69
	global_load_lds_dwordx4 v[158:159], off
	s_mov_b32 m0, s52
	v_lshl_add_u64 v[158:159], s[50:51], 0, v[188:189]
	global_load_lds_dwordx4 v[158:159], off
	s_add_i32 m0, s52, 0x2000
	v_lshl_add_u64 v[158:159], s[50:51], 0, v[148:149]
	global_load_lds_dwordx4 v[158:159], off
	s_mov_b32 m0, s2
	v_lshl_add_u64 v[158:159], v[248:249], 0, s[94:95]
	global_load_lds_dwordx4 v[158:159], off
	s_mov_b32 m0, s4
	v_lshl_add_u64 v[158:159], v[250:251], 0, s[94:95]
	global_load_lds_dwordx4 v[158:159], off
	s_waitcnt vmcnt(8)
	s_waitcnt lgkmcnt(0)
	s_barrier
	s_setprio 1
	s_waitcnt lgkmcnt(0)
	v_mfma_f32_16x16x32_bf16 v[60:63], v[64:67], v[176:179], v[60:63]
	v_mfma_f32_16x16x32_bf16 v[56:59], v[72:75], v[176:179], v[56:59]
	v_mfma_f32_16x16x32_bf16 v[44:47], v[64:67], v[184:187], v[44:47]
	v_mfma_f32_16x16x32_bf16 v[40:43], v[72:75], v[184:187], v[40:43]
	v_mfma_f32_16x16x32_bf16 v[28:31], v[64:67], v[230:233], v[28:31]
	v_mfma_f32_16x16x32_bf16 v[24:27], v[72:75], v[230:233], v[24:27]
	v_mfma_f32_16x16x32_bf16 v[12:15], v[64:67], v[238:241], v[12:15]
	v_mfma_f32_16x16x32_bf16 v[8:11], v[72:75], v[238:241], v[8:11]
	v_mfma_f32_16x16x32_bf16 v[60:63], v[68:71], v[180:183], v[60:63]
	v_mfma_f32_16x16x32_bf16 v[56:59], v[76:79], v[180:183], v[56:59]
	v_mfma_f32_16x16x32_bf16 v[44:47], v[68:71], v[194:197], v[44:47]
	v_mfma_f32_16x16x32_bf16 v[40:43], v[76:79], v[194:197], v[40:43]
	v_mfma_f32_16x16x32_bf16 v[28:31], v[68:71], v[234:237], v[28:31]
	v_mfma_f32_16x16x32_bf16 v[24:27], v[76:79], v[234:237], v[24:27]
	v_mfma_f32_16x16x32_bf16 v[12:15], v[68:71], v[242:245], v[12:15]
	v_mfma_f32_16x16x32_bf16 v[8:11], v[76:79], v[242:245], v[8:11]
	s_setprio 0
	s_setprio 1
	v_mfma_f32_16x16x32_bf16 v[52:55], v[154:157], v[176:179], v[52:55]
	v_mfma_f32_16x16x32_bf16 v[48:51], v[168:171], v[176:179], v[48:51]
	v_mfma_f32_16x16x32_bf16 v[36:39], v[154:157], v[184:187], v[36:39]
	v_mfma_f32_16x16x32_bf16 v[32:35], v[168:171], v[184:187], v[32:35]
	v_mfma_f32_16x16x32_bf16 v[20:23], v[154:157], v[230:233], v[20:23]
	v_mfma_f32_16x16x32_bf16 v[16:19], v[168:171], v[230:233], v[16:19]
	v_mfma_f32_16x16x32_bf16 v[4:7], v[154:157], v[238:241], v[4:7]
	v_mfma_f32_16x16x32_bf16 v[0:3], v[168:171], v[238:241], v[0:3]
	v_mfma_f32_16x16x32_bf16 v[52:55], v[164:167], v[180:183], v[52:55]
	v_mfma_f32_16x16x32_bf16 v[48:51], v[172:175], v[180:183], v[48:51]
	v_mfma_f32_16x16x32_bf16 v[36:39], v[164:167], v[194:197], v[36:39]
	v_mfma_f32_16x16x32_bf16 v[32:35], v[172:175], v[194:197], v[32:35]
	v_mfma_f32_16x16x32_bf16 v[20:23], v[164:167], v[234:237], v[20:23]
	v_mfma_f32_16x16x32_bf16 v[16:19], v[172:175], v[234:237], v[16:19]
	v_mfma_f32_16x16x32_bf16 v[4:7], v[164:167], v[242:245], v[4:7]
	v_mfma_f32_16x16x32_bf16 v[0:3], v[172:175], v[242:245], v[0:3]
	s_setprio 0
	s_barrier
	s_add_i32 s59, s59, 2
	s_add_u32 s8, s8, 0x100
	s_addc_u32 s9, s9, 0
	s_add_u32 s55, s55, 0x100
	s_addc_u32 s58, s58, 0
	s_cmp_gt_u32 s59, 13
	s_cbranch_scc0 .LBB0_171
	s_and_b64 vcc, exec, s[30:31]
	s_cbranch_vccz .LBB0_174
	s_barrier

; #define PG8_STAGE(bufoff, gbase, voff) do { _Pragma("unroll") for (int _i = 0; _i < 2; ++_i) \
;         __builtin_amdgcn_global_load_lds((const unsigned*)((const char*)(gbase) + (voff)[_i]), (PG8_LAS unsigned*)(lds + (bufoff) + ldsw + _i * 8192), 16, 0, 0); } while (0)
; #define PG8_LDA(dst, b, h) do { _Pragma("unroll") for (int m = 0; m < 4; ++m) _Pragma("unroll") for (int k = 0; k < 2; ++k) dst[m][k] = *(const PG8_LAS bf16x8*)(lds + PG8_SA(b, h) + aoff + m * 2048 + k * 1024); } while (0)
; #define PG8_LDB(dst, b, h) do { _Pragma("unroll") for (int n = 0; n < 2; ++n) _Pragma("unroll") for (int k = 0; k < 2; ++k) dst[n][k] = *(const PG8_LAS bf16x8*)(lds + PG8_SB(b, h) + boff + n * 2048 + k * 1024); } while (0)
; #define PG8_MMA(ai, bj, At, Bt) do { __builtin_amdgcn_s_setprio(1); _Pragma("unroll") for (int m = 0; m < 4; ++m) _Pragma("unroll") for (int n = 0; n < 2; ++n) _Pragma("unroll") for (int k = 0; k < 2; ++k) \
;         acc[ai][bj][m][n] = __builtin_amdgcn_mfma_f32_16x16x32_bf16(Bt[n][k], At[m][k], acc[ai][bj][m][n], 0, 0, 0); __builtin_amdgcn_s_setprio(0); } while (0)
; #define PG8_WAIT_V(n) asm volatile("s_waitcnt vmcnt(" #n ")" ::: "memory")
; #define PG8_BAR __builtin_amdgcn_s_barrier()
; template <class Epi, class Sched, bool ALIGN_EPI = false, bool SP2 = false>
; __device__ __forceinline__ void gemm_phase(PG8_LAS unsigned char* lds, const Gemm g, const Sched& S, const Epi& E) {
;     ...
;         for (int t = 0; t < nt; t += 2) {
;             const bool last = (t == nt - 2);
;             const char* a1 = cA + (size_t)(t + 1) * kstep;
;             const char* a2 = last ? nA : cA + (size_t)(t + 2) * kstep; const char* b2 = last ? nB : cB + (size_t)(t + 2) * kstep;
;             const char* a3 = a2 + kstep; const char* b3 = b2 + kstep;
;             if (last && has_next) S.a_ready(nxt);
;             if constexpr (SP2) {
;             PG8_LDB(B0, 0, 0); PG8_LDB(B1, 0, 1); PG8_SCHED; PG8_LDA(At, 0, 0); PG8_STAGE(PG8_SA(1, 1), a1 + hstepA, voffA);
;             PG8_WAIT_V(8); PG8_WAIT_L(0); PG8_BAR; PG8_MMA(0, 0, At, B0); PG8_MMA(0, 1, At, B1); PG8_BAR; PG8_SCHED;
;             PG8_LDA(At, 0, 1); PG8_STAGE(PG8_SB(0, 0), b2, voffB); PG8_STAGE(PG8_SB(0, 1), b2 + hstepB, voffB); PG8_STAGE(PG8_SA(0, 0), a2, voffA);
;             PG8_WAIT_V(8); PG8_WAIT_L(0); PG8_BAR; PG8_MMA(1, 0, At, B0); PG8_MMA(1, 1, At, B1); PG8_BAR; PG8_SCHED;
.LBB0_712:
	v_add_u32_e32 v154, 0x10000, v144
	v_add_u32_e32 v170, 0x14000, v144
	ds_read_b128 v[138:141], v154
	ds_read_b128 v[146:149], v154 offset:1024
	ds_read_b128 v[150:153], v154 offset:2048
	ds_read_b128 v[154:157], v154 offset:3072
	ds_read_b128 v[158:161], v170
	ds_read_b128 v[162:165], v170 offset:1024
	ds_read_b128 v[166:169], v170 offset:2048
	ds_read_b128 v[170:173], v170 offset:3072
	ds_read_b128 v[174:177], v145
	ds_read_b128 v[178:181], v145 offset:1024
	ds_read_b128 v[182:185], v145 offset:2048
	ds_read_b128 v[192:195], v145 offset:3072
	ds_read_b128 v[230:233], v145 offset:4096
	ds_read_b128 v[234:237], v145 offset:5120
	ds_read_b128 v[238:241], v145 offset:6144
	ds_read_b128 v[242:245], v145 offset:7168
	s_add_u32 s28, s26, 0xfffc0080
	s_addc_u32 s29, s27, -1
	s_add_i32 s33, 0, 0x10000
	s_cmp_eq_u32 s19, 12
	s_cselect_b32 s31, s1, s29
	s_cselect_b32 s30, s2, s28
	s_cselect_b32 s29, s3, s17
	s_cselect_b32 s28, s4, s9
	s_add_i32 s51, 0, 0x14000
	s_add_i32 m0, s25, 0xc000
	v_lshl_add_u64 v[186:187], s[26:27], 0, v[134:135]
	global_load_lds_dwordx4 v[186:187], off
	s_add_i32 m0, s25, 0xe000
	v_lshl_add_u64 v[186:187], s[26:27], 0, v[136:137]
	global_load_lds_dwordx4 v[186:187], off
	s_waitcnt vmcnt(8)
	s_waitcnt lgkmcnt(0)
	s_barrier
	s_setprio 1
	s_waitcnt lgkmcnt(0)
	v_mfma_f32_16x16x32_bf16 v[124:127], v[138:141], v[174:177], v[124:127]
	v_mfma_f32_16x16x32_bf16 v[120:123], v[150:153], v[174:177], v[120:123]
	v_mfma_f32_16x16x32_bf16 v[108:111], v[138:141], v[182:185], v[108:111]
	v_mfma_f32_16x16x32_bf16 v[104:107], v[150:153], v[182:185], v[104:107]
	v_mfma_f32_16x16x32_bf16 v[92:95], v[138:141], v[230:233], v[92:95]
	v_mfma_f32_16x16x32_bf16 v[88:91], v[150:153], v[230:233], v[88:91]
	v_mfma_f32_16x16x32_bf16 v[76:79], v[138:141], v[238:241], v[76:79]
	v_mfma_f32_16x16x32_bf16 v[72:75], v[150:153], v[238:241], v[72:75]
	v_mfma_f32_16x16x32_bf16 v[124:127], v[146:149], v[178:181], v[124:127]
	v_mfma_f32_16x16x32_bf16 v[120:123], v[154:157], v[178:181], v[120:123]
	v_mfma_f32_16x16x32_bf16 v[108:111], v[146:149], v[192:195], v[108:111]
	v_mfma_f32_16x16x32_bf16 v[104:107], v[154:157], v[192:195], v[104:107]
	v_mfma_f32_16x16x32_bf16 v[92:95], v[146:149], v[234:237], v[92:95]
	v_mfma_f32_16x16x32_bf16 v[88:91], v[154:157], v[234:237], v[88:91]
	v_mfma_f32_16x16x32_bf16 v[76:79], v[146:149], v[242:245], v[76:79]
	v_mfma_f32_16x16x32_bf16 v[72:75], v[154:157], v[242:245], v[72:75]
	s_setprio 0
	s_setprio 1
	v_mfma_f32_16x16x32_bf16 v[116:119], v[158:161], v[174:177], v[116:119]
	v_mfma_f32_16x16x32_bf16 v[112:115], v[166:169], v[174:177], v[112:115]
	v_mfma_f32_16x16x32_bf16 v[100:103], v[158:161], v[182:185], v[100:103]
	v_mfma_f32_16x16x32_bf16 v[96:99], v[166:169], v[182:185], v[96:99]
	v_mfma_f32_16x16x32_bf16 v[84:87], v[158:161], v[230:233], v[84:87]
	v_mfma_f32_16x16x32_bf16 v[80:83], v[166:169], v[230:233], v[80:83]
	v_mfma_f32_16x16x32_bf16 v[68:71], v[158:161], v[238:241], v[68:71]
	v_mfma_f32_16x16x32_bf16 v[64:67], v[166:169], v[238:241], v[64:67]
	v_mfma_f32_16x16x32_bf16 v[116:119], v[162:165], v[178:181], v[116:119]
	v_mfma_f32_16x16x32_bf16 v[112:115], v[170:173], v[178:181], v[112:115]
	v_mfma_f32_16x16x32_bf16 v[100:103], v[162:165], v[192:195], v[100:103]
	v_mfma_f32_16x16x32_bf16 v[96:99], v[170:173], v[192:195], v[96:99]
	v_mfma_f32_16x16x32_bf16 v[84:87], v[162:165], v[234:237], v[84:87]
	v_mfma_f32_16x16x32_bf16 v[80:83], v[170:173], v[234:237], v[80:83]
	v_mfma_f32_16x16x32_bf16 v[68:71], v[162:165], v[242:245], v[68:71]
	v_mfma_f32_16x16x32_bf16 v[64:67], v[170:173], v[242:245], v[64:67]
	s_setprio 0
	s_barrier
	ds_read_b128 v[174:177], v145 offset:16384
	ds_read_b128 v[178:181], v145 offset:17408
	ds_read_b128 v[182:185], v145 offset:18432
	ds_read_b128 v[192:195], v145 offset:19456
	ds_read_b128 v[230:233], v145 offset:20480
	ds_read_b128 v[234:237], v145 offset:21504
	ds_read_b128 v[238:241], v145 offset:22528
	ds_read_b128 v[242:245], v145 offset:23552
	s_add_i32 s33, s33, s39
	s_mov_b32 m0, s33
	v_lshl_add_u64 v[186:187], s[28:29], 0, v[188:189]
	global_load_lds_dwordx4 v[186:187], off
	s_add_i32 m0, s33, 0x2000
	s_add_u32 s52, s28, 0x40000
	v_lshl_add_u64 v[196:197], s[28:29], 0, v[132:133]
	s_addc_u32 s53, s29, 0
	s_add_i32 s33, s51, s39
	global_load_lds_dwordx4 v[196:197], off
	v_lshl_add_u64 v[246:247], s[52:53], 0, v[188:189]
	s_mov_b32 m0, s33
	v_lshl_add_u64 v[248:249], s[30:31], 0, v[130:131]
	global_load_lds_dwordx4 v[246:247], off
	s_add_i32 m0, s33, 0x2000
	v_lshl_add_u64 v[246:247], s[52:53], 0, v[132:133]
	global_load_lds_dwordx4 v[246:247], off
	s_mov_b32 m0, s25
	v_lshl_add_u64 v[246:247], s[30:31], 0, v[128:129]
	global_load_lds_dwordx4 v[246:247], off
	s_mov_b32 m0, s40
	s_nop 0
	global_load_lds_dwordx4 v[248:249], off
	s_waitcnt vmcnt(8)
	s_waitcnt lgkmcnt(0)
	s_barrier
; #define PG8_STAGE(bufoff, gbase, voff) do { _Pragma("unroll") for (int _i = 0; _i < 2; ++_i) \
;         __builtin_amdgcn_global_load_lds((const unsigned*)((const char*)(gbase) + (voff)[_i]), (PG8_LAS unsigned*)(lds + (bufoff) + ldsw + _i * 8192), 16, 0, 0); } while (0)
; #define PG8_LDA(dst, b, h) do { _Pragma("unroll") for (int m = 0; m < 4; ++m) _Pragma("unroll") for (int k = 0; k < 2; ++k) dst[m][k] = *(const PG8_LAS bf16x8*)(lds + PG8_SA(b, h) + aoff + m * 2048 + k * 1024); } while (0)
; #define PG8_LDB(dst, b, h) do { _Pragma("unroll") for (int n = 0; n < 2; ++n) _Pragma("unroll") for (int k = 0; k < 2; ++k) dst[n][k] = *(const PG8_LAS bf16x8*)(lds + PG8_SB(b, h) + boff + n * 2048 + k * 1024); } while (0)
; #define PG8_MMA(ai, bj, At, Bt) do { __builtin_amdgcn_s_setprio(1); _Pragma("unroll") for (int m = 0; m < 4; ++m) _Pragma("unroll") for (int n = 0; n < 2; ++n) _Pragma("unroll") for (int k = 0; k < 2; ++k) \
;         acc[ai][bj][m][n] = __builtin_amdgcn_mfma_f32_16x16x32_bf16(Bt[n][k], At[m][k], acc[ai][bj][m][n], 0, 0, 0); __builtin_amdgcn_s_setprio(0); } while (0)
; #define PG8_WAIT_V(n) asm volatile("s_waitcnt vmcnt(" #n ")" ::: "memory")
; #define PG8_WAIT_L(n) asm volatile("s_waitcnt lgkmcnt(" #n ")" ::: "memory")
; #define PG8_BAR __builtin_amdgcn_s_barrier()
; #define PG8_SCHED __builtin_amdgcn_sched_barrier(0)
; template <class Epi, class Sched, bool ALIGN_EPI = false, bool SP2 = false>
; __device__ __forceinline__ void gemm_phase(PG8_LAS unsigned char* lds, const Gemm g, const Sched& S, const Epi& E) {
;     ...
;             PG8_WAIT_V(8); PG8_WAIT_L(0); PG8_BAR; PG8_MMA(1, 0, At, B0); PG8_MMA(1, 1, At, B1); PG8_BAR; PG8_SCHED;
;             PG8_LDB(B0, 1, 0); PG8_LDB(B1, 1, 1); PG8_SCHED; PG8_LDA(At, 1, 0); PG8_STAGE(PG8_SA(0, 1), a2 + hstepA, voffA);
;             PG8_WAIT_V(8); PG8_WAIT_L(0); PG8_BAR; PG8_MMA(0, 0, At, B0); PG8_MMA(0, 1, At, B1); PG8_BAR; PG8_SCHED;
	s_setprio 1
	s_waitcnt lgkmcnt(0)
	v_mfma_f32_16x16x32_bf16 v[60:63], v[138:141], v[174:177], v[60:63]
	v_mfma_f32_16x16x32_bf16 v[56:59], v[150:153], v[174:177], v[56:59]
	v_mfma_f32_16x16x32_bf16 v[44:47], v[138:141], v[182:185], v[44:47]
	v_mfma_f32_16x16x32_bf16 v[40:43], v[150:153], v[182:185], v[40:43]
	v_mfma_f32_16x16x32_bf16 v[28:31], v[138:141], v[230:233], v[28:31]
	v_mfma_f32_16x16x32_bf16 v[24:27], v[150:153], v[230:233], v[24:27]
	v_mfma_f32_16x16x32_bf16 v[12:15], v[138:141], v[238:241], v[12:15]
	v_mfma_f32_16x16x32_bf16 v[8:11], v[150:153], v[238:241], v[8:11]
	v_mfma_f32_16x16x32_bf16 v[60:63], v[146:149], v[178:181], v[60:63]
	v_mfma_f32_16x16x32_bf16 v[56:59], v[154:157], v[178:181], v[56:59]
	v_mfma_f32_16x16x32_bf16 v[44:47], v[146:149], v[192:195], v[44:47]
	v_mfma_f32_16x16x32_bf16 v[40:43], v[154:157], v[192:195], v[40:43]
	v_mfma_f32_16x16x32_bf16 v[28:31], v[146:149], v[234:237], v[28:31]
	v_mfma_f32_16x16x32_bf16 v[24:27], v[154:157], v[234:237], v[24:27]
	v_mfma_f32_16x16x32_bf16 v[12:15], v[146:149], v[242:245], v[12:15]
	v_mfma_f32_16x16x32_bf16 v[8:11], v[154:157], v[242:245], v[8:11]
	s_setprio 0
	s_setprio 1
	v_mfma_f32_16x16x32_bf16 v[52:55], v[158:161], v[174:177], v[52:55]
	v_mfma_f32_16x16x32_bf16 v[48:51], v[166:169], v[174:177], v[48:51]
	v_mfma_f32_16x16x32_bf16 v[36:39], v[158:161], v[182:185], v[36:39]
	v_mfma_f32_16x16x32_bf16 v[32:35], v[166:169], v[182:185], v[32:35]
	v_mfma_f32_16x16x32_bf16 v[20:23], v[158:161], v[230:233], v[20:23]
	v_mfma_f32_16x16x32_bf16 v[16:19], v[166:169], v[230:233], v[16:19]
	v_mfma_f32_16x16x32_bf16 v[4:7], v[158:161], v[238:241], v[4:7]
	v_mfma_f32_16x16x32_bf16 v[0:3], v[166:169], v[238:241], v[0:3]
	v_mfma_f32_16x16x32_bf16 v[52:55], v[162:165], v[178:181], v[52:55]
	v_mfma_f32_16x16x32_bf16 v[48:51], v[170:173], v[178:181], v[48:51]
	v_mfma_f32_16x16x32_bf16 v[36:39], v[162:165], v[192:195], v[36:39]
	v_mfma_f32_16x16x32_bf16 v[32:35], v[170:173], v[192:195], v[32:35]
	v_mfma_f32_16x16x32_bf16 v[20:23], v[162:165], v[234:237], v[20:23]
	v_mfma_f32_16x16x32_bf16 v[16:19], v[170:173], v[234:237], v[16:19]
	v_mfma_f32_16x16x32_bf16 v[4:7], v[162:165], v[242:245], v[4:7]
	v_mfma_f32_16x16x32_bf16 v[0:3], v[170:173], v[242:245], v[0:3]
	s_setprio 0
	s_barrier
	v_add_u32_e32 v154, 0x18000, v144
	v_add_u32_e32 v170, 0x1c000, v144
	ds_read_b128 v[138:141], v154
	ds_read_b128 v[146:149], v154 offset:1024
	ds_read_b128 v[150:153], v154 offset:2048
	ds_read_b128 v[154:157], v154 offset:3072
	ds_read_b128 v[158:161], v170
	ds_read_b128 v[162:165], v170 offset:1024
	ds_read_b128 v[166:169], v170 offset:2048
	ds_read_b128 v[170:173], v170 offset:3072
	ds_read_b128 v[174:177], v145 offset:32768
	ds_read_b128 v[178:181], v145 offset:33792
	ds_read_b128 v[182:185], v145 offset:34816
	ds_read_b128 v[192:195], v145 offset:35840
	ds_read_b128 v[230:233], v145 offset:36864
	ds_read_b128 v[234:237], v145 offset:37888
	ds_read_b128 v[238:241], v145 offset:38912
	ds_read_b128 v[242:245], v145 offset:39936
	s_add_i32 s33, 0, 0x18000
	s_add_i32 s51, 0, 0x1c000
	s_add_u32 s30, s30, 0x40000
	s_addc_u32 s31, s31, 0
	s_mov_b32 m0, s41
	v_lshl_add_u64 v[250:251], s[30:31], 0, v[128:129]
	global_load_lds_dwordx4 v[250:251], off
	s_mov_b32 m0, s42
	v_lshl_add_u64 v[250:251], s[30:31], 0, v[130:131]
	global_load_lds_dwordx4 v[250:251], off
	s_waitcnt vmcnt(8)
	s_waitcnt lgkmcnt(0)
	s_barrier
	s_setprio 1
	s_waitcnt lgkmcnt(0)
	v_mfma_f32_16x16x32_bf16 v[124:127], v[138:141], v[174:177], v[124:127]
	v_mfma_f32_16x16x32_bf16 v[120:123], v[150:153], v[174:177], v[120:123]
	v_mfma_f32_16x16x32_bf16 v[108:111], v[138:141], v[182:185], v[108:111]
	v_mfma_f32_16x16x32_bf16 v[104:107], v[150:153], v[182:185], v[104:107]
	v_mfma_f32_16x16x32_bf16 v[92:95], v[138:141], v[230:233], v[92:95]
	v_mfma_f32_16x16x32_bf16 v[88:91], v[150:153], v[230:233], v[88:91]
	v_mfma_f32_16x16x32_bf16 v[76:79], v[138:141], v[238:241], v[76:79]
	v_mfma_f32_16x16x32_bf16 v[72:75], v[150:153], v[238:241], v[72:75]
	v_mfma_f32_16x16x32_bf16 v[124:127], v[146:149], v[178:181], v[124:127]
	v_mfma_f32_16x16x32_bf16 v[120:123], v[154:157], v[178:181], v[120:123]
	v_mfma_f32_16x16x32_bf16 v[108:111], v[146:149], v[192:195], v[108:111]
	v_mfma_f32_16x16x32_bf16 v[104:107], v[154:157], v[192:195], v[104:107]
	v_mfma_f32_16x16x32_bf16 v[92:95], v[146:149], v[234:237], v[92:95]
	v_mfma_f32_16x16x32_bf16 v[88:91], v[154:157], v[234:237], v[88:91]
	v_mfma_f32_16x16x32_bf16 v[76:79], v[146:149], v[242:245], v[76:79]
	v_mfma_f32_16x16x32_bf16 v[72:75], v[154:157], v[242:245], v[72:75]
	s_setprio 0
	s_setprio 1
	v_mfma_f32_16x16x32_bf16 v[116:119], v[158:161], v[174:177], v[116:119]
	v_mfma_f32_16x16x32_bf16 v[112:115], v[166:169], v[174:177], v[112:115]
	v_mfma_f32_16x16x32_bf16 v[100:103], v[158:161], v[182:185], v[100:103]
	v_mfma_f32_16x16x32_bf16 v[96:99], v[166:169], v[182:185], v[96:99]
	v_mfma_f32_16x16x32_bf16 v[84:87], v[158:161], v[230:233], v[84:87]
	v_mfma_f32_16x16x32_bf16 v[80:83], v[166:169], v[230:233], v[80:83]
	v_mfma_f32_16x16x32_bf16 v[68:71], v[158:161], v[238:241], v[68:71]
	v_mfma_f32_16x16x32_bf16 v[64:67], v[166:169], v[238:241], v[64:67]
	v_mfma_f32_16x16x32_bf16 v[116:119], v[162:165], v[178:181], v[116:119]
	v_mfma_f32_16x16x32_bf16 v[112:115], v[170:173], v[178:181], v[112:115]
	v_mfma_f32_16x16x32_bf16 v[100:103], v[162:165], v[192:195], v[100:103]
	v_mfma_f32_16x16x32_bf16 v[96:99], v[170:173], v[192:195], v[96:99]
	v_mfma_f32_16x16x32_bf16 v[84:87], v[162:165], v[234:237], v[84:87]
	v_mfma_f32_16x16x32_bf16 v[80:83], v[170:173], v[234:237], v[80:83]
	v_mfma_f32_16x16x32_bf16 v[68:71], v[162:165], v[242:245], v[68:71]
	v_mfma_f32_16x16x32_bf16 v[64:67], v[170:173], v[242:245], v[64:67]
	s_setprio 0
	s_barrier
; #define PG8_STAGE(bufoff, gbase, voff) do { _Pragma("unroll") for (int _i = 0; _i < 2; ++_i) \
;         __builtin_amdgcn_global_load_lds((const unsigned*)((const char*)(gbase) + (voff)[_i]), (PG8_LAS unsigned*)(lds + (bufoff) + ldsw + _i * 8192), 16, 0, 0); } while (0)
; #define PG8_LDA(dst, b, h) do { _Pragma("unroll") for (int m = 0; m < 4; ++m) _Pragma("unroll") for (int k = 0; k < 2; ++k) dst[m][k] = *(const PG8_LAS bf16x8*)(lds + PG8_SA(b, h) + aoff + m * 2048 + k * 1024); } while (0)
; #define PG8_MMA(ai, bj, At, Bt) do { __builtin_amdgcn_s_setprio(1); _Pragma("unroll") for (int m = 0; m < 4; ++m) _Pragma("unroll") for (int n = 0; n < 2; ++n) _Pragma("unroll") for (int k = 0; k < 2; ++k) \
;         acc[ai][bj][m][n] = __builtin_amdgcn_mfma_f32_16x16x32_bf16(Bt[n][k], At[m][k], acc[ai][bj][m][n], 0, 0, 0); __builtin_amdgcn_s_setprio(0); } while (0)
; #define PG8_WAIT_V(n) asm volatile("s_waitcnt vmcnt(" #n ")" ::: "memory")
; #define PG8_WAIT_L(n) asm volatile("s_waitcnt lgkmcnt(" #n ")" ::: "memory")
; #define PG8_BAR __builtin_amdgcn_s_barrier()
; #define PG8_SCHED __builtin_amdgcn_sched_barrier(0)
; template <class Epi, class Sched, bool ALIGN_EPI = false, bool SP2 = false>
; __device__ __forceinline__ void gemm_phase(PG8_LAS unsigned char* lds, const Gemm g, const Sched& S, const Epi& E) {
;     ...
;         for (int t = 0; t < nt; t += 2) {
;     ...
;             PG8_LDA(At, 1, 1); PG8_STAGE(PG8_SB(1, 0), b3, voffB); PG8_STAGE(PG8_SB(1, 1), b3 + hstepB, voffB); PG8_STAGE(PG8_SA(1, 0), a3, voffA);
;             PG8_WAIT_V(8); PG8_WAIT_L(0); PG8_BAR; PG8_MMA(1, 0, At, B0); PG8_MMA(1, 1, At, B1); PG8_BAR; PG8_SCHED;
	ds_read_b128 v[174:177], v145 offset:49152
	ds_read_b128 v[178:181], v145 offset:50176
	ds_read_b128 v[182:185], v145 offset:51200
	ds_read_b128 v[192:195], v145 offset:52224
	ds_read_b128 v[230:233], v145 offset:53248
	ds_read_b128 v[234:237], v145 offset:54272
	ds_read_b128 v[238:241], v145 offset:55296
	ds_read_b128 v[242:245], v145 offset:56320
	s_add_i32 s30, s33, s39
	s_mov_b32 m0, s30
	v_lshl_add_u64 v[186:187], v[186:187], 0, s[94:95]
	global_load_lds_dwordx4 v[186:187], off
	s_add_i32 m0, s30, 0x2000
	s_add_u32 s28, s28, 0x40080
	v_lshl_add_u64 v[186:187], v[196:197], 0, s[94:95]
	s_addc_u32 s29, s29, 0
	s_add_i32 s30, s51, s39
	global_load_lds_dwordx4 v[186:187], off
	s_mov_b32 m0, s30
	v_lshl_add_u64 v[186:187], s[28:29], 0, v[188:189]
	global_load_lds_dwordx4 v[186:187], off
	s_add_i32 m0, s30, 0x2000
	v_lshl_add_u64 v[186:187], s[28:29], 0, v[132:133]
	global_load_lds_dwordx4 v[186:187], off
	s_mov_b32 m0, s47
	v_lshl_add_u64 v[186:187], v[246:247], 0, s[94:95]
	global_load_lds_dwordx4 v[186:187], off
	s_mov_b32 m0, s48
	v_lshl_add_u64 v[186:187], v[248:249], 0, s[94:95]
	global_load_lds_dwordx4 v[186:187], off
	s_waitcnt vmcnt(8)
	s_waitcnt lgkmcnt(0)
	s_barrier
	s_setprio 1
	s_waitcnt lgkmcnt(0)
	v_mfma_f32_16x16x32_bf16 v[60:63], v[138:141], v[174:177], v[60:63]
	v_mfma_f32_16x16x32_bf16 v[56:59], v[150:153], v[174:177], v[56:59]
	v_mfma_f32_16x16x32_bf16 v[44:47], v[138:141], v[182:185], v[44:47]
	v_mfma_f32_16x16x32_bf16 v[40:43], v[150:153], v[182:185], v[40:43]
	v_mfma_f32_16x16x32_bf16 v[28:31], v[138:141], v[230:233], v[28:31]
	v_mfma_f32_16x16x32_bf16 v[24:27], v[150:153], v[230:233], v[24:27]
	v_mfma_f32_16x16x32_bf16 v[12:15], v[138:141], v[238:241], v[12:15]
	v_mfma_f32_16x16x32_bf16 v[8:11], v[150:153], v[238:241], v[8:11]
	v_mfma_f32_16x16x32_bf16 v[60:63], v[146:149], v[178:181], v[60:63]
	v_mfma_f32_16x16x32_bf16 v[56:59], v[154:157], v[178:181], v[56:59]
	v_mfma_f32_16x16x32_bf16 v[44:47], v[146:149], v[192:195], v[44:47]
	v_mfma_f32_16x16x32_bf16 v[40:43], v[154:157], v[192:195], v[40:43]
	v_mfma_f32_16x16x32_bf16 v[28:31], v[146:149], v[234:237], v[28:31]
	v_mfma_f32_16x16x32_bf16 v[24:27], v[154:157], v[234:237], v[24:27]
	v_mfma_f32_16x16x32_bf16 v[12:15], v[146:149], v[242:245], v[12:15]
	v_mfma_f32_16x16x32_bf16 v[8:11], v[154:157], v[242:245], v[8:11]
	s_setprio 0
	s_setprio 1
	v_mfma_f32_16x16x32_bf16 v[52:55], v[158:161], v[174:177], v[52:55]
	v_mfma_f32_16x16x32_bf16 v[48:51], v[166:169], v[174:177], v[48:51]
	v_mfma_f32_16x16x32_bf16 v[36:39], v[158:161], v[182:185], v[36:39]
	v_mfma_f32_16x16x32_bf16 v[32:35], v[166:169], v[182:185], v[32:35]
	v_mfma_f32_16x16x32_bf16 v[20:23], v[158:161], v[230:233], v[20:23]
	v_mfma_f32_16x16x32_bf16 v[16:19], v[166:169], v[230:233], v[16:19]
	v_mfma_f32_16x16x32_bf16 v[4:7], v[158:161], v[238:241], v[4:7]
	v_mfma_f32_16x16x32_bf16 v[0:3], v[166:169], v[238:241], v[0:3]
	v_mfma_f32_16x16x32_bf16 v[52:55], v[162:165], v[178:181], v[52:55]
	v_mfma_f32_16x16x32_bf16 v[48:51], v[170:173], v[178:181], v[48:51]
	v_mfma_f32_16x16x32_bf16 v[36:39], v[162:165], v[192:195], v[36:39]
	v_mfma_f32_16x16x32_bf16 v[32:35], v[170:173], v[192:195], v[32:35]
	v_mfma_f32_16x16x32_bf16 v[20:23], v[162:165], v[234:237], v[20:23]
	v_mfma_f32_16x16x32_bf16 v[16:19], v[170:173], v[234:237], v[16:19]
	v_mfma_f32_16x16x32_bf16 v[4:7], v[162:165], v[242:245], v[4:7]
	v_mfma_f32_16x16x32_bf16 v[0:3], v[170:173], v[242:245], v[0:3]
	s_setprio 0
	s_barrier
	s_add_i32 s19, s19, 2
	s_add_u32 s26, s26, 0x100
	s_addc_u32 s27, s27, 0
	s_add_u32 s9, s9, 0x100
	s_addc_u32 s17, s17, 0
	s_cmp_gt_u32 s19, 13
	s_cbranch_scc0 .LBB0_712
	s_and_b64 vcc, exec, s[14:15]
	s_cbranch_vccz .LBB0_715
	s_barrier

; #define PG8_STAGE(bufoff, gbase, voff) do { _Pragma("unroll") for (int _i = 0; _i < 2; ++_i) \
;         __builtin_amdgcn_global_load_lds((const unsigned*)((const char*)(gbase) + (voff)[_i]), (PG8_LAS unsigned*)(lds + (bufoff) + ldsw + _i * 8192), 16, 0, 0); } while (0)
; #define PG8_LDA(dst, b, h) do { _Pragma("unroll") for (int m = 0; m < 4; ++m) _Pragma("unroll") for (int k = 0; k < 2; ++k) dst[m][k] = *(const PG8_LAS bf16x8*)(lds + PG8_SA(b, h) + aoff + m * 2048 + k * 1024); } while (0)
; #define PG8_LDB(dst, b, h) do { _Pragma("unroll") for (int n = 0; n < 2; ++n) _Pragma("unroll") for (int k = 0; k < 2; ++k) dst[n][k] = *(const PG8_LAS bf16x8*)(lds + PG8_SB(b, h) + boff + n * 2048 + k * 1024); } while (0)
; #define PG8_MMA(ai, bj, At, Bt) do { __builtin_amdgcn_s_setprio(1); _Pragma("unroll") for (int m = 0; m < 4; ++m) _Pragma("unroll") for (int n = 0; n < 2; ++n) _Pragma("unroll") for (int k = 0; k < 2; ++k) \
;         acc[ai][bj][m][n] = __builtin_amdgcn_mfma_f32_16x16x32_bf16(Bt[n][k], At[m][k], acc[ai][bj][m][n], 0, 0, 0); __builtin_amdgcn_s_setprio(0); } while (0)
; #define PG8_WAIT_V(n) asm volatile("s_waitcnt vmcnt(" #n ")" ::: "memory")
; #define PG8_BAR __builtin_amdgcn_s_barrier()
; template <class Epi, class Sched, bool ALIGN_EPI = false, bool SP2 = false>
; __device__ __forceinline__ void gemm_phase(PG8_LAS unsigned char* lds, const Gemm g, const Sched& S, const Epi& E) {
;     ...
;         for (int t = 0; t < nt; t += 2) {
;             const bool last = (t == nt - 2);
;             const char* a1 = cA + (size_t)(t + 1) * kstep;
;             const char* a2 = last ? nA : cA + (size_t)(t + 2) * kstep; const char* b2 = last ? nB : cB + (size_t)(t + 2) * kstep;
;             const char* a3 = a2 + kstep; const char* b3 = b2 + kstep;
;             if (last && has_next) S.a_ready(nxt);
;             if constexpr (SP2) {
;             PG8_LDB(B0, 0, 0); PG8_LDB(B1, 0, 1); PG8_SCHED; PG8_LDA(At, 0, 0); PG8_STAGE(PG8_SA(1, 1), a1 + hstepA, voffA);
;             PG8_WAIT_V(8); PG8_WAIT_L(0); PG8_BAR; PG8_MMA(0, 0, At, B0); PG8_MMA(0, 1, At, B1); PG8_BAR; PG8_SCHED;
;             PG8_LDA(At, 0, 1); PG8_STAGE(PG8_SB(0, 0), b2, voffB); PG8_STAGE(PG8_SB(0, 1), b2 + hstepB, voffB); PG8_STAGE(PG8_SA(0, 0), a2, voffA);
;             PG8_WAIT_V(8); PG8_WAIT_L(0); PG8_BAR; PG8_MMA(1, 0, At, B0); PG8_MMA(1, 1, At, B1); PG8_BAR; PG8_SCHED;
.LBB0_1642:
	v_add_u32_e32 v150, 0x10000, v148
	v_add_u32_e32 v166, 0x14000, v148
	ds_read_b128 v[128:131], v150
	ds_read_b128 v[138:141], v150 offset:1024
	ds_read_b128 v[142:145], v150 offset:2048
	ds_read_b128 v[150:153], v150 offset:3072
	ds_read_b128 v[154:157], v166
	ds_read_b128 v[158:161], v166 offset:1024
	ds_read_b128 v[162:165], v166 offset:2048
	ds_read_b128 v[166:169], v166 offset:3072
	ds_read_b128 v[170:173], v149
	ds_read_b128 v[174:177], v149 offset:1024
	ds_read_b128 v[178:181], v149 offset:2048
	ds_read_b128 v[182:185], v149 offset:3072
	ds_read_b128 v[192:195], v149 offset:4096
	ds_read_b128 v[230:233], v149 offset:5120
	ds_read_b128 v[234:237], v149 offset:6144
	ds_read_b128 v[238:241], v149 offset:7168
	s_add_i32 s74, s28, 2
	s_add_u32 s75, s26, 0x80
	s_addc_u32 s29, s27, 0
	s_add_i32 s78, 0, 0x10000
	s_cmp_eq_u32 s54, s28
	s_cselect_b32 s29, s9, s29
	s_cselect_b32 s28, s8, s75
	s_cselect_b32 s77, s25, s73
	s_cselect_b32 s76, s24, s72
	s_add_i32 s75, 0, 0x14000
	s_add_i32 m0, s36, 0xc000
	v_lshl_add_u64 v[186:187], s[26:27], 0, v[134:135]
	global_load_lds_dwordx4 v[186:187], off
	s_add_i32 m0, s36, 0xe000
	v_lshl_add_u64 v[186:187], s[26:27], 0, v[136:137]
	global_load_lds_dwordx4 v[186:187], off
	s_waitcnt vmcnt(8)
	s_waitcnt lgkmcnt(0)
	s_barrier
	s_setprio 1
	s_waitcnt lgkmcnt(0)
	v_mfma_f32_16x16x32_bf16 v[124:127], v[128:131], v[170:173], v[124:127]
	v_mfma_f32_16x16x32_bf16 v[96:99], v[142:145], v[170:173], v[96:99]
	v_mfma_f32_16x16x32_bf16 v[120:123], v[128:131], v[178:181], v[120:123]
	v_mfma_f32_16x16x32_bf16 v[92:95], v[142:145], v[178:181], v[92:95]
	v_mfma_f32_16x16x32_bf16 v[116:119], v[128:131], v[192:195], v[116:119]
	v_mfma_f32_16x16x32_bf16 v[88:91], v[142:145], v[192:195], v[88:91]
	v_mfma_f32_16x16x32_bf16 v[112:115], v[128:131], v[234:237], v[112:115]
	v_mfma_f32_16x16x32_bf16 v[80:83], v[142:145], v[234:237], v[80:83]
	v_mfma_f32_16x16x32_bf16 v[124:127], v[138:141], v[174:177], v[124:127]
	v_mfma_f32_16x16x32_bf16 v[96:99], v[150:153], v[174:177], v[96:99]
	v_mfma_f32_16x16x32_bf16 v[120:123], v[138:141], v[182:185], v[120:123]
	v_mfma_f32_16x16x32_bf16 v[92:95], v[150:153], v[182:185], v[92:95]
	v_mfma_f32_16x16x32_bf16 v[116:119], v[138:141], v[230:233], v[116:119]
	v_mfma_f32_16x16x32_bf16 v[88:91], v[150:153], v[230:233], v[88:91]
	v_mfma_f32_16x16x32_bf16 v[112:115], v[138:141], v[238:241], v[112:115]
	v_mfma_f32_16x16x32_bf16 v[80:83], v[150:153], v[238:241], v[80:83]
	s_setprio 0
	s_setprio 1
	v_mfma_f32_16x16x32_bf16 v[72:75], v[154:157], v[170:173], v[72:75]
	v_mfma_f32_16x16x32_bf16 v[44:47], v[162:165], v[170:173], v[44:47]
	v_mfma_f32_16x16x32_bf16 v[64:67], v[154:157], v[178:181], v[64:67]
	v_mfma_f32_16x16x32_bf16 v[36:39], v[162:165], v[178:181], v[36:39]
	v_mfma_f32_16x16x32_bf16 v[56:59], v[154:157], v[192:195], v[56:59]
	v_mfma_f32_16x16x32_bf16 v[28:31], v[162:165], v[192:195], v[28:31]
	v_mfma_f32_16x16x32_bf16 v[48:51], v[154:157], v[234:237], v[48:51]
	v_mfma_f32_16x16x32_bf16 v[20:23], v[162:165], v[234:237], v[20:23]
	v_mfma_f32_16x16x32_bf16 v[72:75], v[158:161], v[174:177], v[72:75]
	v_mfma_f32_16x16x32_bf16 v[44:47], v[166:169], v[174:177], v[44:47]
	v_mfma_f32_16x16x32_bf16 v[64:67], v[158:161], v[182:185], v[64:67]
	v_mfma_f32_16x16x32_bf16 v[36:39], v[166:169], v[182:185], v[36:39]
	v_mfma_f32_16x16x32_bf16 v[56:59], v[158:161], v[230:233], v[56:59]
	v_mfma_f32_16x16x32_bf16 v[28:31], v[166:169], v[230:233], v[28:31]
	v_mfma_f32_16x16x32_bf16 v[48:51], v[158:161], v[238:241], v[48:51]
	v_mfma_f32_16x16x32_bf16 v[20:23], v[166:169], v[238:241], v[20:23]
	s_setprio 0
	s_barrier
	ds_read_b128 v[170:173], v149 offset:16384
	ds_read_b128 v[174:177], v149 offset:17408
	ds_read_b128 v[178:181], v149 offset:18432
	ds_read_b128 v[182:185], v149 offset:19456
	ds_read_b128 v[192:195], v149 offset:20480
	ds_read_b128 v[230:233], v149 offset:21504
	ds_read_b128 v[234:237], v149 offset:22528
	ds_read_b128 v[238:241], v149 offset:23552
	s_add_i32 s78, s78, s30
	s_mov_b32 m0, s78
	v_lshl_add_u64 v[186:187], s[76:77], 0, v[188:189]
	global_load_lds_dwordx4 v[186:187], off
	s_add_i32 m0, s78, 0x2000
	v_lshl_add_u64 v[196:197], s[76:77], 0, v[132:133]
	s_add_u32 s76, s76, s44
	s_addc_u32 s77, s77, 0
	s_add_i32 s75, s75, s30
	global_load_lds_dwordx4 v[196:197], off
	v_lshl_add_u64 v[242:243], s[76:77], 0, v[188:189]
	s_mov_b32 m0, s75
	v_lshl_add_u64 v[244:245], s[76:77], 0, v[132:133]
	global_load_lds_dwordx4 v[242:243], off
	s_add_i32 m0, s75, 0x2000
	v_lshl_add_u64 v[246:247], s[28:29], 0, v[188:189]
	global_load_lds_dwordx4 v[244:245], off
	s_mov_b32 m0, s36
	v_lshl_add_u64 v[248:249], s[28:29], 0, v[132:133]
	global_load_lds_dwordx4 v[246:247], off
	s_mov_b32 m0, s37
	s_nop 0
	global_load_lds_dwordx4 v[248:249], off
	s_waitcnt vmcnt(8)
	s_waitcnt lgkmcnt(0)
	s_barrier
; #define PG8_STAGE(bufoff, gbase, voff) do { _Pragma("unroll") for (int _i = 0; _i < 2; ++_i) \
;         __builtin_amdgcn_global_load_lds((const unsigned*)((const char*)(gbase) + (voff)[_i]), (PG8_LAS unsigned*)(lds + (bufoff) + ldsw + _i * 8192), 16, 0, 0); } while (0)
; #define PG8_LDA(dst, b, h) do { _Pragma("unroll") for (int m = 0; m < 4; ++m) _Pragma("unroll") for (int k = 0; k < 2; ++k) dst[m][k] = *(const PG8_LAS bf16x8*)(lds + PG8_SA(b, h) + aoff + m * 2048 + k * 1024); } while (0)
; #define PG8_LDB(dst, b, h) do { _Pragma("unroll") for (int n = 0; n < 2; ++n) _Pragma("unroll") for (int k = 0; k < 2; ++k) dst[n][k] = *(const PG8_LAS bf16x8*)(lds + PG8_SB(b, h) + boff + n * 2048 + k * 1024); } while (0)
; #define PG8_MMA(ai, bj, At, Bt) do { __builtin_amdgcn_s_setprio(1); _Pragma("unroll") for (int m = 0; m < 4; ++m) _Pragma("unroll") for (int n = 0; n < 2; ++n) _Pragma("unroll") for (int k = 0; k < 2; ++k) \
;         acc[ai][bj][m][n] = __builtin_amdgcn_mfma_f32_16x16x32_bf16(Bt[n][k], At[m][k], acc[ai][bj][m][n], 0, 0, 0); __builtin_amdgcn_s_setprio(0); } while (0)
; #define PG8_WAIT_V(n) asm volatile("s_waitcnt vmcnt(" #n ")" ::: "memory")
; #define PG8_WAIT_L(n) asm volatile("s_waitcnt lgkmcnt(" #n ")" ::: "memory")
; #define PG8_BAR __builtin_amdgcn_s_barrier()
; #define PG8_SCHED __builtin_amdgcn_sched_barrier(0)
; template <class Epi, class Sched, bool ALIGN_EPI = false, bool SP2 = false>
; __device__ __forceinline__ void gemm_phase(PG8_LAS unsigned char* lds, const Gemm g, const Sched& S, const Epi& E) {
;     ...
;             PG8_WAIT_V(8); PG8_WAIT_L(0); PG8_BAR; PG8_MMA(1, 0, At, B0); PG8_MMA(1, 1, At, B1); PG8_BAR; PG8_SCHED;
;             PG8_LDB(B0, 1, 0); PG8_LDB(B1, 1, 1); PG8_SCHED; PG8_LDA(At, 1, 0); PG8_STAGE(PG8_SA(0, 1), a2 + hstepA, voffA);
;             PG8_WAIT_V(8); PG8_WAIT_L(0); PG8_BAR; PG8_MMA(0, 0, At, B0); PG8_MMA(0, 1, At, B1); PG8_BAR; PG8_SCHED;
	s_setprio 1
	s_waitcnt lgkmcnt(0)
	v_mfma_f32_16x16x32_bf16 v[108:111], v[128:131], v[170:173], v[108:111]
	v_mfma_f32_16x16x32_bf16 v[76:79], v[142:145], v[170:173], v[76:79]
	v_mfma_f32_16x16x32_bf16 v[104:107], v[128:131], v[178:181], v[104:107]
	v_mfma_f32_16x16x32_bf16 v[68:71], v[142:145], v[178:181], v[68:71]
	v_mfma_f32_16x16x32_bf16 v[100:103], v[128:131], v[192:195], v[100:103]
	v_mfma_f32_16x16x32_bf16 v[60:63], v[142:145], v[192:195], v[60:63]
	v_mfma_f32_16x16x32_bf16 v[84:87], v[128:131], v[234:237], v[84:87]
	v_mfma_f32_16x16x32_bf16 v[52:55], v[142:145], v[234:237], v[52:55]
	v_mfma_f32_16x16x32_bf16 v[108:111], v[138:141], v[174:177], v[108:111]
	v_mfma_f32_16x16x32_bf16 v[76:79], v[150:153], v[174:177], v[76:79]
	v_mfma_f32_16x16x32_bf16 v[104:107], v[138:141], v[182:185], v[104:107]
	v_mfma_f32_16x16x32_bf16 v[68:71], v[150:153], v[182:185], v[68:71]
	v_mfma_f32_16x16x32_bf16 v[100:103], v[138:141], v[230:233], v[100:103]
	v_mfma_f32_16x16x32_bf16 v[60:63], v[150:153], v[230:233], v[60:63]
	v_mfma_f32_16x16x32_bf16 v[84:87], v[138:141], v[238:241], v[84:87]
	v_mfma_f32_16x16x32_bf16 v[52:55], v[150:153], v[238:241], v[52:55]
	s_setprio 0
	s_setprio 1
	v_mfma_f32_16x16x32_bf16 v[40:43], v[154:157], v[170:173], v[40:43]
	v_mfma_f32_16x16x32_bf16 v[12:15], v[162:165], v[170:173], v[12:15]
	v_mfma_f32_16x16x32_bf16 v[32:35], v[154:157], v[178:181], v[32:35]
	v_mfma_f32_16x16x32_bf16 v[8:11], v[162:165], v[178:181], v[8:11]
	v_mfma_f32_16x16x32_bf16 v[24:27], v[154:157], v[192:195], v[24:27]
	v_mfma_f32_16x16x32_bf16 v[4:7], v[162:165], v[192:195], v[4:7]
	v_mfma_f32_16x16x32_bf16 v[16:19], v[154:157], v[234:237], v[16:19]
	v_mfma_f32_16x16x32_bf16 v[0:3], v[162:165], v[234:237], v[0:3]
	v_mfma_f32_16x16x32_bf16 v[40:43], v[158:161], v[174:177], v[40:43]
	v_mfma_f32_16x16x32_bf16 v[12:15], v[166:169], v[174:177], v[12:15]
	v_mfma_f32_16x16x32_bf16 v[32:35], v[158:161], v[182:185], v[32:35]
	v_mfma_f32_16x16x32_bf16 v[8:11], v[166:169], v[182:185], v[8:11]
	v_mfma_f32_16x16x32_bf16 v[24:27], v[158:161], v[230:233], v[24:27]
	v_mfma_f32_16x16x32_bf16 v[4:7], v[166:169], v[230:233], v[4:7]
	v_mfma_f32_16x16x32_bf16 v[16:19], v[158:161], v[238:241], v[16:19]
	v_mfma_f32_16x16x32_bf16 v[0:3], v[166:169], v[238:241], v[0:3]
	s_setprio 0
	s_barrier
	v_add_u32_e32 v150, 0x18000, v148
	v_add_u32_e32 v166, 0x1c000, v148
	ds_read_b128 v[128:131], v150
	ds_read_b128 v[138:141], v150 offset:1024
	ds_read_b128 v[142:145], v150 offset:2048
	ds_read_b128 v[150:153], v150 offset:3072
	ds_read_b128 v[154:157], v166
	ds_read_b128 v[158:161], v166 offset:1024
	ds_read_b128 v[162:165], v166 offset:2048
	ds_read_b128 v[166:169], v166 offset:3072
	ds_read_b128 v[170:173], v149 offset:32768
	ds_read_b128 v[174:177], v149 offset:33792
	ds_read_b128 v[178:181], v149 offset:34816
	ds_read_b128 v[182:185], v149 offset:35840
	ds_read_b128 v[192:195], v149 offset:36864
	ds_read_b128 v[230:233], v149 offset:37888
	ds_read_b128 v[234:237], v149 offset:38912
	ds_read_b128 v[238:241], v149 offset:39936
	s_add_i32 s75, 0, 0x18000
	s_add_i32 s76, 0, 0x1c000
	s_add_u32 s28, s28, s44
	s_addc_u32 s29, s29, 0
	s_mov_b32 m0, s46
	v_lshl_add_u64 v[250:251], s[28:29], 0, v[188:189]
	global_load_lds_dwordx4 v[250:251], off
	s_mov_b32 m0, s47
	v_lshl_add_u64 v[250:251], s[28:29], 0, v[132:133]
	global_load_lds_dwordx4 v[250:251], off
	s_waitcnt vmcnt(8)
	s_waitcnt lgkmcnt(0)
	s_barrier
	s_setprio 1
	s_waitcnt lgkmcnt(0)
	v_mfma_f32_16x16x32_bf16 v[124:127], v[128:131], v[170:173], v[124:127]
	v_mfma_f32_16x16x32_bf16 v[96:99], v[142:145], v[170:173], v[96:99]
	v_mfma_f32_16x16x32_bf16 v[120:123], v[128:131], v[178:181], v[120:123]
	v_mfma_f32_16x16x32_bf16 v[92:95], v[142:145], v[178:181], v[92:95]
	v_mfma_f32_16x16x32_bf16 v[116:119], v[128:131], v[192:195], v[116:119]
	v_mfma_f32_16x16x32_bf16 v[88:91], v[142:145], v[192:195], v[88:91]
	v_mfma_f32_16x16x32_bf16 v[112:115], v[128:131], v[234:237], v[112:115]
	v_mfma_f32_16x16x32_bf16 v[80:83], v[142:145], v[234:237], v[80:83]
	v_mfma_f32_16x16x32_bf16 v[124:127], v[138:141], v[174:177], v[124:127]
	v_mfma_f32_16x16x32_bf16 v[96:99], v[150:153], v[174:177], v[96:99]
	v_mfma_f32_16x16x32_bf16 v[120:123], v[138:141], v[182:185], v[120:123]
	v_mfma_f32_16x16x32_bf16 v[92:95], v[150:153], v[182:185], v[92:95]
	v_mfma_f32_16x16x32_bf16 v[116:119], v[138:141], v[230:233], v[116:119]
	v_mfma_f32_16x16x32_bf16 v[88:91], v[150:153], v[230:233], v[88:91]
	v_mfma_f32_16x16x32_bf16 v[112:115], v[138:141], v[238:241], v[112:115]
	v_mfma_f32_16x16x32_bf16 v[80:83], v[150:153], v[238:241], v[80:83]
	s_setprio 0
	s_setprio 1
	v_mfma_f32_16x16x32_bf16 v[72:75], v[154:157], v[170:173], v[72:75]
	v_mfma_f32_16x16x32_bf16 v[44:47], v[162:165], v[170:173], v[44:47]
	v_mfma_f32_16x16x32_bf16 v[64:67], v[154:157], v[178:181], v[64:67]
	v_mfma_f32_16x16x32_bf16 v[36:39], v[162:165], v[178:181], v[36:39]
	v_mfma_f32_16x16x32_bf16 v[56:59], v[154:157], v[192:195], v[56:59]
	v_mfma_f32_16x16x32_bf16 v[28:31], v[162:165], v[192:195], v[28:31]
	v_mfma_f32_16x16x32_bf16 v[48:51], v[154:157], v[234:237], v[48:51]
	v_mfma_f32_16x16x32_bf16 v[20:23], v[162:165], v[234:237], v[20:23]
	v_mfma_f32_16x16x32_bf16 v[72:75], v[158:161], v[174:177], v[72:75]
	v_mfma_f32_16x16x32_bf16 v[44:47], v[166:169], v[174:177], v[44:47]
	v_mfma_f32_16x16x32_bf16 v[64:67], v[158:161], v[182:185], v[64:67]
	v_mfma_f32_16x16x32_bf16 v[36:39], v[166:169], v[182:185], v[36:39]
	v_mfma_f32_16x16x32_bf16 v[56:59], v[158:161], v[230:233], v[56:59]
	v_mfma_f32_16x16x32_bf16 v[28:31], v[166:169], v[230:233], v[28:31]
	v_mfma_f32_16x16x32_bf16 v[48:51], v[158:161], v[238:241], v[48:51]
	v_mfma_f32_16x16x32_bf16 v[20:23], v[166:169], v[238:241], v[20:23]
	s_setprio 0
	s_barrier
; #define PG8_STAGE(bufoff, gbase, voff) do { _Pragma("unroll") for (int _i = 0; _i < 2; ++_i) \
;         __builtin_amdgcn_global_load_lds((const unsigned*)((const char*)(gbase) + (voff)[_i]), (PG8_LAS unsigned*)(lds + (bufoff) + ldsw + _i * 8192), 16, 0, 0); } while (0)
; #define PG8_LDA(dst, b, h) do { _Pragma("unroll") for (int m = 0; m < 4; ++m) _Pragma("unroll") for (int k = 0; k < 2; ++k) dst[m][k] = *(const PG8_LAS bf16x8*)(lds + PG8_SA(b, h) + aoff + m * 2048 + k * 1024); } while (0)
; #define PG8_MMA(ai, bj, At, Bt) do { __builtin_amdgcn_s_setprio(1); _Pragma("unroll") for (int m = 0; m < 4; ++m) _Pragma("unroll") for (int n = 0; n < 2; ++n) _Pragma("unroll") for (int k = 0; k < 2; ++k) \
;         acc[ai][bj][m][n] = __builtin_amdgcn_mfma_f32_16x16x32_bf16(Bt[n][k], At[m][k], acc[ai][bj][m][n], 0, 0, 0); __builtin_amdgcn_s_setprio(0); } while (0)
; #define PG8_WAIT_V(n) asm volatile("s_waitcnt vmcnt(" #n ")" ::: "memory")
; #define PG8_WAIT_L(n) asm volatile("s_waitcnt lgkmcnt(" #n ")" ::: "memory")
; #define PG8_BAR __builtin_amdgcn_s_barrier()
; #define PG8_SCHED __builtin_amdgcn_sched_barrier(0)
; template <class Epi, class Sched, bool ALIGN_EPI = false, bool SP2 = false>
; __device__ __forceinline__ void gemm_phase(PG8_LAS unsigned char* lds, const Gemm g, const Sched& S, const Epi& E) {
;     ...
;             PG8_LDA(At, 1, 1); PG8_STAGE(PG8_SB(1, 0), b3, voffB); PG8_STAGE(PG8_SB(1, 1), b3 + hstepB, voffB); PG8_STAGE(PG8_SA(1, 0), a3, voffA);
;             PG8_WAIT_V(8); PG8_WAIT_L(0); PG8_BAR; PG8_MMA(1, 0, At, B0); PG8_MMA(1, 1, At, B1); PG8_BAR; PG8_SCHED;
	ds_read_b128 v[170:173], v149 offset:49152
	ds_read_b128 v[174:177], v149 offset:50176
	ds_read_b128 v[178:181], v149 offset:51200
	ds_read_b128 v[182:185], v149 offset:52224
	ds_read_b128 v[192:195], v149 offset:53248
	ds_read_b128 v[230:233], v149 offset:54272
	ds_read_b128 v[234:237], v149 offset:55296
	ds_read_b128 v[238:241], v149 offset:56320
	s_add_i32 s28, s75, s30
	s_mov_b32 m0, s28
	v_lshl_add_u64 v[186:187], v[186:187], 0, s[94:95]
	global_load_lds_dwordx4 v[186:187], off
	v_lshl_add_u64 v[186:187], v[196:197], 0, s[94:95]
	s_add_i32 m0, s28, 0x2000
	s_add_i32 s28, s76, s30
	global_load_lds_dwordx4 v[186:187], off
	s_mov_b32 m0, s28
	v_lshl_add_u64 v[186:187], v[242:243], 0, s[94:95]
	global_load_lds_dwordx4 v[186:187], off
	s_add_i32 m0, s28, 0x2000
	v_lshl_add_u64 v[186:187], v[244:245], 0, s[94:95]
	global_load_lds_dwordx4 v[186:187], off
	s_mov_b32 m0, s62
	v_lshl_add_u64 v[186:187], v[246:247], 0, s[94:95]
	global_load_lds_dwordx4 v[186:187], off
	s_mov_b32 m0, s63
	v_lshl_add_u64 v[186:187], v[248:249], 0, s[94:95]
	global_load_lds_dwordx4 v[186:187], off
	s_waitcnt vmcnt(8)
	s_waitcnt lgkmcnt(0)
	s_barrier
	s_setprio 1
	s_waitcnt lgkmcnt(0)
	v_mfma_f32_16x16x32_bf16 v[108:111], v[128:131], v[170:173], v[108:111]
	v_mfma_f32_16x16x32_bf16 v[76:79], v[142:145], v[170:173], v[76:79]
	v_mfma_f32_16x16x32_bf16 v[104:107], v[128:131], v[178:181], v[104:107]
	v_mfma_f32_16x16x32_bf16 v[68:71], v[142:145], v[178:181], v[68:71]
	v_mfma_f32_16x16x32_bf16 v[100:103], v[128:131], v[192:195], v[100:103]
	v_mfma_f32_16x16x32_bf16 v[60:63], v[142:145], v[192:195], v[60:63]
	v_mfma_f32_16x16x32_bf16 v[84:87], v[128:131], v[234:237], v[84:87]
	v_mfma_f32_16x16x32_bf16 v[52:55], v[142:145], v[234:237], v[52:55]
	v_mfma_f32_16x16x32_bf16 v[108:111], v[138:141], v[174:177], v[108:111]
	v_mfma_f32_16x16x32_bf16 v[76:79], v[150:153], v[174:177], v[76:79]
	v_mfma_f32_16x16x32_bf16 v[104:107], v[138:141], v[182:185], v[104:107]
	v_mfma_f32_16x16x32_bf16 v[68:71], v[150:153], v[182:185], v[68:71]
	v_mfma_f32_16x16x32_bf16 v[100:103], v[138:141], v[230:233], v[100:103]
	v_mfma_f32_16x16x32_bf16 v[60:63], v[150:153], v[230:233], v[60:63]
	v_mfma_f32_16x16x32_bf16 v[84:87], v[138:141], v[238:241], v[84:87]
	v_mfma_f32_16x16x32_bf16 v[52:55], v[150:153], v[238:241], v[52:55]
	s_setprio 0
	s_setprio 1
	v_mfma_f32_16x16x32_bf16 v[40:43], v[154:157], v[170:173], v[40:43]
	v_mfma_f32_16x16x32_bf16 v[12:15], v[162:165], v[170:173], v[12:15]
	v_mfma_f32_16x16x32_bf16 v[32:35], v[154:157], v[178:181], v[32:35]
	v_mfma_f32_16x16x32_bf16 v[8:11], v[162:165], v[178:181], v[8:11]
	v_mfma_f32_16x16x32_bf16 v[24:27], v[154:157], v[192:195], v[24:27]
	v_mfma_f32_16x16x32_bf16 v[4:7], v[162:165], v[192:195], v[4:7]
	v_mfma_f32_16x16x32_bf16 v[16:19], v[154:157], v[234:237], v[16:19]
	v_mfma_f32_16x16x32_bf16 v[0:3], v[162:165], v[234:237], v[0:3]
	v_mfma_f32_16x16x32_bf16 v[40:43], v[158:161], v[174:177], v[40:43]
	v_mfma_f32_16x16x32_bf16 v[12:15], v[166:169], v[174:177], v[12:15]
	v_mfma_f32_16x16x32_bf16 v[32:35], v[158:161], v[182:185], v[32:35]
	v_mfma_f32_16x16x32_bf16 v[8:11], v[166:169], v[182:185], v[8:11]
	v_mfma_f32_16x16x32_bf16 v[24:27], v[158:161], v[230:233], v[24:27]
	v_mfma_f32_16x16x32_bf16 v[4:7], v[166:169], v[230:233], v[4:7]
	v_mfma_f32_16x16x32_bf16 v[16:19], v[158:161], v[238:241], v[16:19]
	v_mfma_f32_16x16x32_bf16 v[0:3], v[166:169], v[238:241], v[0:3]
	s_setprio 0
	s_barrier
	s_add_u32 s26, s26, 0x100
	s_addc_u32 s27, s27, 0
	s_add_u32 s72, s72, 0x100
	s_addc_u32 s73, s73, 0
	s_cmp_ge_u32 s74, s52
	s_mov_b32 s28, s74
	s_cbranch_scc0 .LBB0_1642
	s_and_b64 vcc, exec, s[14:15]
	s_cbranch_vccz .LBB0_1645
	s_barrier

; #define PG8_STAGE(bufoff, gbase, voff) do { _Pragma("unroll") for (int _i = 0; _i < 2; ++_i) \
;         __builtin_amdgcn_global_load_lds((const unsigned*)((const char*)(gbase) + (voff)[_i]), (PG8_LAS unsigned*)(lds + (bufoff) + ldsw + _i * 8192), 16, 0, 0); } while (0)
; #define PG8_LDA(dst, b, h) do { _Pragma("unroll") for (int m = 0; m < 4; ++m) _Pragma("unroll") for (int k = 0; k < 2; ++k) dst[m][k] = *(const PG8_LAS bf16x8*)(lds + PG8_SA(b, h) + aoff + m * 2048 + k * 1024); } while (0)
; #define PG8_LDB(dst, b, h) do { _Pragma("unroll") for (int n = 0; n < 2; ++n) _Pragma("unroll") for (int k = 0; k < 2; ++k) dst[n][k] = *(const PG8_LAS bf16x8*)(lds + PG8_SB(b, h) + boff + n * 2048 + k * 1024); } while (0)
; #define PG8_MMA(ai, bj, At, Bt) do { __builtin_amdgcn_s_setprio(1); _Pragma("unroll") for (int m = 0; m < 4; ++m) _Pragma("unroll") for (int n = 0; n < 2; ++n) _Pragma("unroll") for (int k = 0; k < 2; ++k) \
;         acc[ai][bj][m][n] = __builtin_amdgcn_mfma_f32_16x16x32_bf16(Bt[n][k], At[m][k], acc[ai][bj][m][n], 0, 0, 0); __builtin_amdgcn_s_setprio(0); } while (0)
; #define PG8_WAIT_V(n) asm volatile("s_waitcnt vmcnt(" #n ")" ::: "memory")
; #define PG8_WAIT_L(n) asm volatile("s_waitcnt lgkmcnt(" #n ")" ::: "memory")
; #define PG8_BAR __builtin_amdgcn_s_barrier()
; #define PG8_SCHED __builtin_amdgcn_sched_barrier(0)
; template <class Epi, class Sched, bool ALIGN_EPI = false, bool SP2 = false>
; __device__ __forceinline__ void gemm_phase(PG8_LAS unsigned char* lds, const Gemm g, const Sched& S, const Epi& E) {
;     ...
;             const bool last = (t == nt - 2);
;             const char* a1 = cA + (size_t)(t + 1) * kstep;
;             const char* a2 = last ? nA : cA + (size_t)(t + 2) * kstep; const char* b2 = last ? nB : cB + (size_t)(t + 2) * kstep;
;             const char* a3 = a2 + kstep; const char* b3 = b2 + kstep;
;             if (last && has_next) S.a_ready(nxt);
;             if constexpr (SP2) {
;             PG8_LDB(B0, 0, 0); PG8_LDB(B1, 0, 1); PG8_SCHED; PG8_LDA(At, 0, 0); PG8_STAGE(PG8_SA(1, 1), a1 + hstepA, voffA);
;             PG8_WAIT_V(8); PG8_WAIT_L(0); PG8_BAR; PG8_MMA(0, 0, At, B0); PG8_MMA(0, 1, At, B1); PG8_BAR; PG8_SCHED;
;             PG8_LDA(At, 0, 1); PG8_STAGE(PG8_SB(0, 0), b2, voffB); PG8_STAGE(PG8_SB(0, 1), b2 + hstepB, voffB); PG8_STAGE(PG8_SA(0, 0), a2, voffA);
.LBB0_1800:
	v_add_u32_e32 v140, 0x10000, v229
	v_add_u32_e32 v156, 0x14000, v229
	ds_read_b128 v[128:131], v140
	ds_read_b128 v[132:135], v140 offset:1024
	ds_read_b128 v[136:139], v140 offset:2048
	ds_read_b128 v[140:143], v140 offset:3072
	ds_read_b128 v[144:147], v156
	ds_read_b128 v[148:151], v156 offset:1024
	ds_read_b128 v[152:155], v156 offset:2048
	ds_read_b128 v[156:159], v156 offset:3072
	ds_read_b128 v[160:163], v230
	ds_read_b128 v[164:167], v230 offset:1024
	ds_read_b128 v[178:181], v230 offset:2048
	ds_read_b128 v[182:185], v230 offset:3072
	ds_read_b128 v[192:195], v230 offset:4096
	ds_read_b128 v[232:235], v230 offset:5120
	ds_read_b128 v[236:239], v230 offset:6144
	ds_read_b128 v[240:243], v230 offset:7168
	s_add_u32 s10, s8, 0xfffc0080
	s_addc_u32 s11, s9, -1
	s_add_i32 s71, 0, 0x10000
	s_cmp_eq_u32 s70, 12
	s_cselect_b32 s45, s13, s11
	s_cselect_b32 s44, s15, s10
	s_cselect_b32 s11, s35, s47
	s_cselect_b32 s10, s37, s46
	s_add_i32 s74, 0, 0x14000
	s_add_i32 m0, s54, 0xc000
	v_lshl_add_u64 v[186:187], s[8:9], 0, v[174:175]
	global_load_lds_dwordx4 v[186:187], off
	s_add_i32 m0, s54, 0xe000
	v_lshl_add_u64 v[186:187], s[8:9], 0, v[176:177]
	global_load_lds_dwordx4 v[186:187], off
	s_waitcnt vmcnt(8)
	s_waitcnt lgkmcnt(0)
	s_barrier
	s_setprio 1
	s_waitcnt lgkmcnt(0)
	v_mfma_f32_16x16x32_bf16 v[124:127], v[128:131], v[160:163], v[124:127]
	v_mfma_f32_16x16x32_bf16 v[60:63], v[136:139], v[160:163], v[60:63]
	v_mfma_f32_16x16x32_bf16 v[120:123], v[128:131], v[178:181], v[120:123]
	v_mfma_f32_16x16x32_bf16 v[56:59], v[136:139], v[178:181], v[56:59]
	v_mfma_f32_16x16x32_bf16 v[108:111], v[128:131], v[192:195], v[108:111]
	v_mfma_f32_16x16x32_bf16 v[44:47], v[136:139], v[192:195], v[44:47]
	v_mfma_f32_16x16x32_bf16 v[100:103], v[128:131], v[236:239], v[100:103]
	v_mfma_f32_16x16x32_bf16 v[36:39], v[136:139], v[236:239], v[36:39]
	v_mfma_f32_16x16x32_bf16 v[124:127], v[132:135], v[164:167], v[124:127]
	v_mfma_f32_16x16x32_bf16 v[60:63], v[140:143], v[164:167], v[60:63]
	v_mfma_f32_16x16x32_bf16 v[120:123], v[132:135], v[182:185], v[120:123]
	v_mfma_f32_16x16x32_bf16 v[56:59], v[140:143], v[182:185], v[56:59]
	v_mfma_f32_16x16x32_bf16 v[108:111], v[132:135], v[232:235], v[108:111]
	v_mfma_f32_16x16x32_bf16 v[44:47], v[140:143], v[232:235], v[44:47]
	v_mfma_f32_16x16x32_bf16 v[100:103], v[132:135], v[240:243], v[100:103]
	v_mfma_f32_16x16x32_bf16 v[36:39], v[140:143], v[240:243], v[36:39]
	s_setprio 0
	s_setprio 1
	v_mfma_f32_16x16x32_bf16 v[116:119], v[144:147], v[160:163], v[116:119]
	v_mfma_f32_16x16x32_bf16 v[52:55], v[152:155], v[160:163], v[52:55]
	v_mfma_f32_16x16x32_bf16 v[112:115], v[144:147], v[178:181], v[112:115]
	v_mfma_f32_16x16x32_bf16 v[48:51], v[152:155], v[178:181], v[48:51]
	v_mfma_f32_16x16x32_bf16 v[104:107], v[144:147], v[192:195], v[104:107]
	v_mfma_f32_16x16x32_bf16 v[40:43], v[152:155], v[192:195], v[40:43]
	v_mfma_f32_16x16x32_bf16 v[96:99], v[144:147], v[236:239], v[96:99]
	v_mfma_f32_16x16x32_bf16 v[32:35], v[152:155], v[236:239], v[32:35]
	v_mfma_f32_16x16x32_bf16 v[116:119], v[148:151], v[164:167], v[116:119]
	v_mfma_f32_16x16x32_bf16 v[52:55], v[156:159], v[164:167], v[52:55]
	v_mfma_f32_16x16x32_bf16 v[112:115], v[148:151], v[182:185], v[112:115]
	v_mfma_f32_16x16x32_bf16 v[48:51], v[156:159], v[182:185], v[48:51]
	v_mfma_f32_16x16x32_bf16 v[104:107], v[148:151], v[232:235], v[104:107]
	v_mfma_f32_16x16x32_bf16 v[40:43], v[156:159], v[232:235], v[40:43]
	v_mfma_f32_16x16x32_bf16 v[96:99], v[148:151], v[240:243], v[96:99]
	v_mfma_f32_16x16x32_bf16 v[32:35], v[156:159], v[240:243], v[32:35]
	s_setprio 0
	s_barrier
	ds_read_b128 v[160:163], v230 offset:16384
	ds_read_b128 v[164:167], v230 offset:17408
	ds_read_b128 v[178:181], v230 offset:18432
	ds_read_b128 v[182:185], v230 offset:19456
	ds_read_b128 v[192:195], v230 offset:20480
	ds_read_b128 v[232:235], v230 offset:21504
	ds_read_b128 v[236:239], v230 offset:22528
	ds_read_b128 v[240:243], v230 offset:23552
	s_add_i32 s71, s71, s53
	s_mov_b32 m0, s71
	v_lshl_add_u64 v[186:187], s[10:11], 0, v[188:189]
	global_load_lds_dwordx4 v[186:187], off
	s_add_i32 m0, s71, 0x2000
	s_add_u32 s72, s10, 0x40000
	v_lshl_add_u64 v[244:245], s[10:11], 0, v[172:173]
	s_addc_u32 s73, s11, 0
	s_add_i32 s71, s74, s53
	global_load_lds_dwordx4 v[244:245], off
	v_lshl_add_u64 v[246:247], s[72:73], 0, v[188:189]
	s_mov_b32 m0, s71
	v_lshl_add_u64 v[248:249], s[44:45], 0, v[170:171]
	global_load_lds_dwordx4 v[246:247], off
	s_add_i32 m0, s71, 0x2000
	v_lshl_add_u64 v[246:247], s[72:73], 0, v[172:173]
	global_load_lds_dwordx4 v[246:247], off
	s_mov_b32 m0, s54
	v_lshl_add_u64 v[246:247], s[44:45], 0, v[168:169]
	global_load_lds_dwordx4 v[246:247], off
	s_mov_b32 m0, s55
	s_nop 0
	global_load_lds_dwordx4 v[248:249], off
	s_waitcnt vmcnt(8)
	s_waitcnt lgkmcnt(0)
	s_barrier
; #define PG8_STAGE(bufoff, gbase, voff) do { _Pragma("unroll") for (int _i = 0; _i < 2; ++_i) \
;         __builtin_amdgcn_global_load_lds((const unsigned*)((const char*)(gbase) + (voff)[_i]), (PG8_LAS unsigned*)(lds + (bufoff) + ldsw + _i * 8192), 16, 0, 0); } while (0)
; #define PG8_LDA(dst, b, h) do { _Pragma("unroll") for (int m = 0; m < 4; ++m) _Pragma("unroll") for (int k = 0; k < 2; ++k) dst[m][k] = *(const PG8_LAS bf16x8*)(lds + PG8_SA(b, h) + aoff + m * 2048 + k * 1024); } while (0)
; #define PG8_LDB(dst, b, h) do { _Pragma("unroll") for (int n = 0; n < 2; ++n) _Pragma("unroll") for (int k = 0; k < 2; ++k) dst[n][k] = *(const PG8_LAS bf16x8*)(lds + PG8_SB(b, h) + boff + n * 2048 + k * 1024); } while (0)
; #define PG8_MMA(ai, bj, At, Bt) do { __builtin_amdgcn_s_setprio(1); _Pragma("unroll") for (int m = 0; m < 4; ++m) _Pragma("unroll") for (int n = 0; n < 2; ++n) _Pragma("unroll") for (int k = 0; k < 2; ++k) \
;         acc[ai][bj][m][n] = __builtin_amdgcn_mfma_f32_16x16x32_bf16(Bt[n][k], At[m][k], acc[ai][bj][m][n], 0, 0, 0); __builtin_amdgcn_s_setprio(0); } while (0)
; #define PG8_WAIT_V(n) asm volatile("s_waitcnt vmcnt(" #n ")" ::: "memory")
; #define PG8_WAIT_L(n) asm volatile("s_waitcnt lgkmcnt(" #n ")" ::: "memory")
; #define PG8_BAR __builtin_amdgcn_s_barrier()
; #define PG8_SCHED __builtin_amdgcn_sched_barrier(0)
; template <class Epi, class Sched, bool ALIGN_EPI = false, bool SP2 = false>
; __device__ __forceinline__ void gemm_phase(PG8_LAS unsigned char* lds, const Gemm g, const Sched& S, const Epi& E) {
;     ...
;             PG8_WAIT_V(8); PG8_WAIT_L(0); PG8_BAR; PG8_MMA(1, 0, At, B0); PG8_MMA(1, 1, At, B1); PG8_BAR; PG8_SCHED;
;             PG8_LDB(B0, 1, 0); PG8_LDB(B1, 1, 1); PG8_SCHED; PG8_LDA(At, 1, 0); PG8_STAGE(PG8_SA(0, 1), a2 + hstepA, voffA);
;             PG8_WAIT_V(8); PG8_WAIT_L(0); PG8_BAR; PG8_MMA(0, 0, At, B0); PG8_MMA(0, 1, At, B1); PG8_BAR; PG8_SCHED;
	s_setprio 1
	s_waitcnt lgkmcnt(0)
	v_mfma_f32_16x16x32_bf16 v[92:95], v[128:131], v[160:163], v[92:95]
	v_mfma_f32_16x16x32_bf16 v[28:31], v[136:139], v[160:163], v[28:31]
	v_mfma_f32_16x16x32_bf16 v[88:91], v[128:131], v[178:181], v[88:91]
	v_mfma_f32_16x16x32_bf16 v[24:27], v[136:139], v[178:181], v[24:27]
	v_mfma_f32_16x16x32_bf16 v[76:79], v[128:131], v[192:195], v[76:79]
	v_mfma_f32_16x16x32_bf16 v[12:15], v[136:139], v[192:195], v[12:15]
	v_mfma_f32_16x16x32_bf16 v[68:71], v[128:131], v[236:239], v[68:71]
	v_mfma_f32_16x16x32_bf16 v[4:7], v[136:139], v[236:239], v[4:7]
	v_mfma_f32_16x16x32_bf16 v[92:95], v[132:135], v[164:167], v[92:95]
	v_mfma_f32_16x16x32_bf16 v[28:31], v[140:143], v[164:167], v[28:31]
	v_mfma_f32_16x16x32_bf16 v[88:91], v[132:135], v[182:185], v[88:91]
	v_mfma_f32_16x16x32_bf16 v[24:27], v[140:143], v[182:185], v[24:27]
	v_mfma_f32_16x16x32_bf16 v[76:79], v[132:135], v[232:235], v[76:79]
	v_mfma_f32_16x16x32_bf16 v[12:15], v[140:143], v[232:235], v[12:15]
	v_mfma_f32_16x16x32_bf16 v[68:71], v[132:135], v[240:243], v[68:71]
	v_mfma_f32_16x16x32_bf16 v[4:7], v[140:143], v[240:243], v[4:7]
	s_setprio 0
	s_setprio 1
	v_mfma_f32_16x16x32_bf16 v[84:87], v[144:147], v[160:163], v[84:87]
	v_mfma_f32_16x16x32_bf16 v[20:23], v[152:155], v[160:163], v[20:23]
	v_mfma_f32_16x16x32_bf16 v[80:83], v[144:147], v[178:181], v[80:83]
	v_mfma_f32_16x16x32_bf16 v[16:19], v[152:155], v[178:181], v[16:19]
	v_mfma_f32_16x16x32_bf16 v[72:75], v[144:147], v[192:195], v[72:75]
	v_mfma_f32_16x16x32_bf16 v[8:11], v[152:155], v[192:195], v[8:11]
	v_mfma_f32_16x16x32_bf16 v[64:67], v[144:147], v[236:239], v[64:67]
	v_mfma_f32_16x16x32_bf16 v[0:3], v[152:155], v[236:239], v[0:3]
	v_mfma_f32_16x16x32_bf16 v[84:87], v[148:151], v[164:167], v[84:87]
	v_mfma_f32_16x16x32_bf16 v[20:23], v[156:159], v[164:167], v[20:23]
	v_mfma_f32_16x16x32_bf16 v[80:83], v[148:151], v[182:185], v[80:83]
	v_mfma_f32_16x16x32_bf16 v[16:19], v[156:159], v[182:185], v[16:19]
	v_mfma_f32_16x16x32_bf16 v[72:75], v[148:151], v[232:235], v[72:75]
	v_mfma_f32_16x16x32_bf16 v[8:11], v[156:159], v[232:235], v[8:11]
	v_mfma_f32_16x16x32_bf16 v[64:67], v[148:151], v[240:243], v[64:67]
	v_mfma_f32_16x16x32_bf16 v[0:3], v[156:159], v[240:243], v[0:3]
	s_setprio 0
	s_barrier
	v_add_u32_e32 v140, 0x18000, v229
	v_add_u32_e32 v156, 0x1c000, v229
	ds_read_b128 v[128:131], v140
	ds_read_b128 v[132:135], v140 offset:1024
	ds_read_b128 v[136:139], v140 offset:2048
	ds_read_b128 v[140:143], v140 offset:3072
	ds_read_b128 v[144:147], v156
	ds_read_b128 v[148:151], v156 offset:1024
	ds_read_b128 v[152:155], v156 offset:2048
	ds_read_b128 v[156:159], v156 offset:3072
	ds_read_b128 v[160:163], v230 offset:32768
	ds_read_b128 v[164:167], v230 offset:33792
	ds_read_b128 v[178:181], v230 offset:34816
	ds_read_b128 v[182:185], v230 offset:35840
	ds_read_b128 v[192:195], v230 offset:36864
	ds_read_b128 v[232:235], v230 offset:37888
	ds_read_b128 v[236:239], v230 offset:38912
	ds_read_b128 v[240:243], v230 offset:39936
	s_add_i32 s71, 0, 0x18000
	s_add_i32 s72, 0, 0x1c000
	s_add_u32 s44, s44, 0x40000
	s_addc_u32 s45, s45, 0
	s_mov_b32 m0, s56
	v_lshl_add_u64 v[250:251], s[44:45], 0, v[168:169]
	global_load_lds_dwordx4 v[250:251], off
	s_mov_b32 m0, s57
	v_lshl_add_u64 v[250:251], s[44:45], 0, v[170:171]
	global_load_lds_dwordx4 v[250:251], off
	s_waitcnt vmcnt(8)
	s_waitcnt lgkmcnt(0)
	s_barrier
	s_setprio 1
	s_waitcnt lgkmcnt(0)
	v_mfma_f32_16x16x32_bf16 v[124:127], v[128:131], v[160:163], v[124:127]
	v_mfma_f32_16x16x32_bf16 v[60:63], v[136:139], v[160:163], v[60:63]
	v_mfma_f32_16x16x32_bf16 v[120:123], v[128:131], v[178:181], v[120:123]
	v_mfma_f32_16x16x32_bf16 v[56:59], v[136:139], v[178:181], v[56:59]
	v_mfma_f32_16x16x32_bf16 v[108:111], v[128:131], v[192:195], v[108:111]
	v_mfma_f32_16x16x32_bf16 v[44:47], v[136:139], v[192:195], v[44:47]
	v_mfma_f32_16x16x32_bf16 v[100:103], v[128:131], v[236:239], v[100:103]
	v_mfma_f32_16x16x32_bf16 v[36:39], v[136:139], v[236:239], v[36:39]
	v_mfma_f32_16x16x32_bf16 v[124:127], v[132:135], v[164:167], v[124:127]
	v_mfma_f32_16x16x32_bf16 v[60:63], v[140:143], v[164:167], v[60:63]
	v_mfma_f32_16x16x32_bf16 v[120:123], v[132:135], v[182:185], v[120:123]
	v_mfma_f32_16x16x32_bf16 v[56:59], v[140:143], v[182:185], v[56:59]
	v_mfma_f32_16x16x32_bf16 v[108:111], v[132:135], v[232:235], v[108:111]
	v_mfma_f32_16x16x32_bf16 v[44:47], v[140:143], v[232:235], v[44:47]
	v_mfma_f32_16x16x32_bf16 v[100:103], v[132:135], v[240:243], v[100:103]
	v_mfma_f32_16x16x32_bf16 v[36:39], v[140:143], v[240:243], v[36:39]
	s_setprio 0
	s_setprio 1
	v_mfma_f32_16x16x32_bf16 v[116:119], v[144:147], v[160:163], v[116:119]
	v_mfma_f32_16x16x32_bf16 v[52:55], v[152:155], v[160:163], v[52:55]
	v_mfma_f32_16x16x32_bf16 v[112:115], v[144:147], v[178:181], v[112:115]
	v_mfma_f32_16x16x32_bf16 v[48:51], v[152:155], v[178:181], v[48:51]
	v_mfma_f32_16x16x32_bf16 v[104:107], v[144:147], v[192:195], v[104:107]
	v_mfma_f32_16x16x32_bf16 v[40:43], v[152:155], v[192:195], v[40:43]
	v_mfma_f32_16x16x32_bf16 v[96:99], v[144:147], v[236:239], v[96:99]
	v_mfma_f32_16x16x32_bf16 v[32:35], v[152:155], v[236:239], v[32:35]
	v_mfma_f32_16x16x32_bf16 v[116:119], v[148:151], v[164:167], v[116:119]
	v_mfma_f32_16x16x32_bf16 v[52:55], v[156:159], v[164:167], v[52:55]
	v_mfma_f32_16x16x32_bf16 v[112:115], v[148:151], v[182:185], v[112:115]
	v_mfma_f32_16x16x32_bf16 v[48:51], v[156:159], v[182:185], v[48:51]
	v_mfma_f32_16x16x32_bf16 v[104:107], v[148:151], v[232:235], v[104:107]
	v_mfma_f32_16x16x32_bf16 v[40:43], v[156:159], v[232:235], v[40:43]
	v_mfma_f32_16x16x32_bf16 v[96:99], v[148:151], v[240:243], v[96:99]
	v_mfma_f32_16x16x32_bf16 v[32:35], v[156:159], v[240:243], v[32:35]
	s_setprio 0
	s_barrier
; #define PG8_STAGE(bufoff, gbase, voff) do { _Pragma("unroll") for (int _i = 0; _i < 2; ++_i) \
;         __builtin_amdgcn_global_load_lds((const unsigned*)((const char*)(gbase) + (voff)[_i]), (PG8_LAS unsigned*)(lds + (bufoff) + ldsw + _i * 8192), 16, 0, 0); } while (0)
; #define PG8_LDA(dst, b, h) do { _Pragma("unroll") for (int m = 0; m < 4; ++m) _Pragma("unroll") for (int k = 0; k < 2; ++k) dst[m][k] = *(const PG8_LAS bf16x8*)(lds + PG8_SA(b, h) + aoff + m * 2048 + k * 1024); } while (0)
; #define PG8_MMA(ai, bj, At, Bt) do { __builtin_amdgcn_s_setprio(1); _Pragma("unroll") for (int m = 0; m < 4; ++m) _Pragma("unroll") for (int n = 0; n < 2; ++n) _Pragma("unroll") for (int k = 0; k < 2; ++k) \
;         acc[ai][bj][m][n] = __builtin_amdgcn_mfma_f32_16x16x32_bf16(Bt[n][k], At[m][k], acc[ai][bj][m][n], 0, 0, 0); __builtin_amdgcn_s_setprio(0); } while (0)
; #define PG8_WAIT_V(n) asm volatile("s_waitcnt vmcnt(" #n ")" ::: "memory")
; #define PG8_WAIT_L(n) asm volatile("s_waitcnt lgkmcnt(" #n ")" ::: "memory")
; #define PG8_BAR __builtin_amdgcn_s_barrier()
; #define PG8_SCHED __builtin_amdgcn_sched_barrier(0)
; template <class Epi, class Sched, bool ALIGN_EPI = false, bool SP2 = false>
; __device__ __forceinline__ void gemm_phase(PG8_LAS unsigned char* lds, const Gemm g, const Sched& S, const Epi& E) {
;     ...
;             PG8_LDA(At, 1, 1); PG8_STAGE(PG8_SB(1, 0), b3, voffB); PG8_STAGE(PG8_SB(1, 1), b3 + hstepB, voffB); PG8_STAGE(PG8_SA(1, 0), a3, voffA);
;             PG8_WAIT_V(8); PG8_WAIT_L(0); PG8_BAR; PG8_MMA(1, 0, At, B0); PG8_MMA(1, 1, At, B1); PG8_BAR; PG8_SCHED;
	ds_read_b128 v[160:163], v230 offset:49152
	ds_read_b128 v[164:167], v230 offset:50176
	ds_read_b128 v[178:181], v230 offset:51200
	ds_read_b128 v[182:185], v230 offset:52224
	ds_read_b128 v[192:195], v230 offset:53248
	ds_read_b128 v[232:235], v230 offset:54272
	ds_read_b128 v[236:239], v230 offset:55296
	ds_read_b128 v[240:243], v230 offset:56320
	s_add_i32 s44, s71, s53
	s_mov_b32 m0, s44
	v_lshl_add_u64 v[186:187], v[186:187], 0, s[94:95]
	global_load_lds_dwordx4 v[186:187], off
	s_add_i32 m0, s44, 0x2000
	s_add_u32 s10, s10, 0x40080
	v_lshl_add_u64 v[186:187], v[244:245], 0, s[94:95]
	s_addc_u32 s11, s11, 0
	s_add_i32 s44, s72, s53
	global_load_lds_dwordx4 v[186:187], off
	s_mov_b32 m0, s44
	v_lshl_add_u64 v[186:187], s[10:11], 0, v[188:189]
	global_load_lds_dwordx4 v[186:187], off
	s_add_i32 m0, s44, 0x2000
	v_lshl_add_u64 v[186:187], s[10:11], 0, v[172:173]
	global_load_lds_dwordx4 v[186:187], off
	s_mov_b32 m0, s60
	v_lshl_add_u64 v[186:187], v[246:247], 0, s[94:95]
	global_load_lds_dwordx4 v[186:187], off
	s_mov_b32 m0, s61
	v_lshl_add_u64 v[186:187], v[248:249], 0, s[94:95]
	global_load_lds_dwordx4 v[186:187], off
	s_waitcnt vmcnt(8)
	s_waitcnt lgkmcnt(0)
	s_barrier
	s_setprio 1
	s_waitcnt lgkmcnt(0)
	v_mfma_f32_16x16x32_bf16 v[92:95], v[128:131], v[160:163], v[92:95]
	v_mfma_f32_16x16x32_bf16 v[28:31], v[136:139], v[160:163], v[28:31]
	v_mfma_f32_16x16x32_bf16 v[88:91], v[128:131], v[178:181], v[88:91]
	v_mfma_f32_16x16x32_bf16 v[24:27], v[136:139], v[178:181], v[24:27]
	v_mfma_f32_16x16x32_bf16 v[76:79], v[128:131], v[192:195], v[76:79]
	v_mfma_f32_16x16x32_bf16 v[12:15], v[136:139], v[192:195], v[12:15]
	v_mfma_f32_16x16x32_bf16 v[68:71], v[128:131], v[236:239], v[68:71]
	v_mfma_f32_16x16x32_bf16 v[4:7], v[136:139], v[236:239], v[4:7]
	v_mfma_f32_16x16x32_bf16 v[92:95], v[132:135], v[164:167], v[92:95]
	v_mfma_f32_16x16x32_bf16 v[28:31], v[140:143], v[164:167], v[28:31]
	v_mfma_f32_16x16x32_bf16 v[88:91], v[132:135], v[182:185], v[88:91]
	v_mfma_f32_16x16x32_bf16 v[24:27], v[140:143], v[182:185], v[24:27]
	v_mfma_f32_16x16x32_bf16 v[76:79], v[132:135], v[232:235], v[76:79]
	v_mfma_f32_16x16x32_bf16 v[12:15], v[140:143], v[232:235], v[12:15]
	v_mfma_f32_16x16x32_bf16 v[68:71], v[132:135], v[240:243], v[68:71]
	v_mfma_f32_16x16x32_bf16 v[4:7], v[140:143], v[240:243], v[4:7]
	s_setprio 0
	s_setprio 1
	v_mfma_f32_16x16x32_bf16 v[84:87], v[144:147], v[160:163], v[84:87]
	v_mfma_f32_16x16x32_bf16 v[20:23], v[152:155], v[160:163], v[20:23]
	v_mfma_f32_16x16x32_bf16 v[80:83], v[144:147], v[178:181], v[80:83]
	v_mfma_f32_16x16x32_bf16 v[16:19], v[152:155], v[178:181], v[16:19]
	v_mfma_f32_16x16x32_bf16 v[72:75], v[144:147], v[192:195], v[72:75]
	v_mfma_f32_16x16x32_bf16 v[8:11], v[152:155], v[192:195], v[8:11]
	v_mfma_f32_16x16x32_bf16 v[64:67], v[144:147], v[236:239], v[64:67]
	v_mfma_f32_16x16x32_bf16 v[0:3], v[152:155], v[236:239], v[0:3]
	v_mfma_f32_16x16x32_bf16 v[84:87], v[148:151], v[164:167], v[84:87]
	v_mfma_f32_16x16x32_bf16 v[20:23], v[156:159], v[164:167], v[20:23]
	v_mfma_f32_16x16x32_bf16 v[80:83], v[148:151], v[182:185], v[80:83]
	v_mfma_f32_16x16x32_bf16 v[16:19], v[156:159], v[182:185], v[16:19]
	v_mfma_f32_16x16x32_bf16 v[72:75], v[148:151], v[232:235], v[72:75]
	v_mfma_f32_16x16x32_bf16 v[8:11], v[156:159], v[232:235], v[8:11]
	v_mfma_f32_16x16x32_bf16 v[64:67], v[148:151], v[240:243], v[64:67]
	v_mfma_f32_16x16x32_bf16 v[0:3], v[156:159], v[240:243], v[0:3]
	s_setprio 0
	s_barrier
	s_add_i32 s70, s70, 2
	s_add_u32 s8, s8, 0x100
	s_addc_u32 s9, s9, 0
	s_add_u32 s46, s46, 0x100
	s_addc_u32 s47, s47, 0
	s_cmp_gt_u32 s70, 13
	s_cbranch_scc0 .LBB0_1800
	s_and_b64 vcc, exec, s[26:27]
	s_cbranch_vccz .LBB0_1803
	s_barrier

; #define PG8_STAGE(bufoff, gbase, voff) do { _Pragma("unroll") for (int _i = 0; _i < 2; ++_i) \
;         __builtin_amdgcn_global_load_lds((const unsigned*)((const char*)(gbase) + (voff)[_i]), (PG8_LAS unsigned*)(lds + (bufoff) + ldsw + _i * 8192), 16, 0, 0); } while (0)
; #define PG8_LDA(dst, b, h) do { _Pragma("unroll") for (int m = 0; m < 4; ++m) _Pragma("unroll") for (int k = 0; k < 2; ++k) dst[m][k] = *(const PG8_LAS bf16x8*)(lds + PG8_SA(b, h) + aoff + m * 2048 + k * 1024); } while (0)
; #define PG8_LDB(dst, b, h) do { _Pragma("unroll") for (int n = 0; n < 2; ++n) _Pragma("unroll") for (int k = 0; k < 2; ++k) dst[n][k] = *(const PG8_LAS bf16x8*)(lds + PG8_SB(b, h) + boff + n * 2048 + k * 1024); } while (0)
; #define PG8_MMA(ai, bj, At, Bt) do { __builtin_amdgcn_s_setprio(1); _Pragma("unroll") for (int m = 0; m < 4; ++m) _Pragma("unroll") for (int n = 0; n < 2; ++n) _Pragma("unroll") for (int k = 0; k < 2; ++k) \
;         acc[ai][bj][m][n] = __builtin_amdgcn_mfma_f32_16x16x32_bf16(Bt[n][k], At[m][k], acc[ai][bj][m][n], 0, 0, 0); __builtin_amdgcn_s_setprio(0); } while (0)
; #define PG8_WAIT_V(n) asm volatile("s_waitcnt vmcnt(" #n ")" ::: "memory")
; #define PG8_WAIT_L(n) asm volatile("s_waitcnt lgkmcnt(" #n ")" ::: "memory")
; #define PG8_BAR __builtin_amdgcn_s_barrier()
; #define PG8_SCHED __builtin_amdgcn_sched_barrier(0)
; template <class Epi, class Sched, bool ALIGN_EPI = false, bool SP2 = false>
; __device__ __forceinline__ void gemm_phase(PG8_LAS unsigned char* lds, const Gemm g, const Sched& S, const Epi& E) {
;     ...
;             const bool last = (t == nt - 2);
;             const char* a1 = cA + (size_t)(t + 1) * kstep;
;             const char* a2 = last ? nA : cA + (size_t)(t + 2) * kstep; const char* b2 = last ? nB : cB + (size_t)(t + 2) * kstep;
;             const char* a3 = a2 + kstep; const char* b3 = b2 + kstep;
;             if (last && has_next) S.a_ready(nxt);
;             if constexpr (SP2) {
;             PG8_LDB(B0, 0, 0); PG8_LDB(B1, 0, 1); PG8_SCHED; PG8_LDA(At, 0, 0); PG8_STAGE(PG8_SA(1, 1), a1 + hstepA, voffA);
;             PG8_WAIT_V(8); PG8_WAIT_L(0); PG8_BAR; PG8_MMA(0, 0, At, B0); PG8_MMA(0, 1, At, B1); PG8_BAR; PG8_SCHED;
;             PG8_LDA(At, 0, 1); PG8_STAGE(PG8_SB(0, 0), b2, voffB); PG8_STAGE(PG8_SB(0, 1), b2 + hstepB, voffB); PG8_STAGE(PG8_SA(0, 0), a2, voffA);
.LBB0_1993:
	v_add_u32_e32 v150, 0x10000, v140
	v_add_u32_e32 v166, 0x14000, v140
	ds_read_b128 v[134:137], v150
	ds_read_b128 v[142:145], v150 offset:1024
	ds_read_b128 v[146:149], v150 offset:2048
	ds_read_b128 v[150:153], v150 offset:3072
	ds_read_b128 v[154:157], v166
	ds_read_b128 v[158:161], v166 offset:1024
	ds_read_b128 v[162:165], v166 offset:2048
	ds_read_b128 v[166:169], v166 offset:3072
	ds_read_b128 v[170:173], v141
	ds_read_b128 v[174:177], v141 offset:1024
	ds_read_b128 v[178:181], v141 offset:2048
	ds_read_b128 v[182:185], v141 offset:3072
	ds_read_b128 v[192:195], v141 offset:4096
	ds_read_b128 v[230:233], v141 offset:5120
	ds_read_b128 v[234:237], v141 offset:6144
	ds_read_b128 v[238:241], v141 offset:7168
	s_add_u32 s24, s22, 0x100
	s_addc_u32 s25, s23, 0
	s_add_i32 s68, 0, 0x10000
	s_cmp_eq_u32 s67, 40
	s_cselect_b32 s29, s9, s25
	s_cselect_b32 s28, s8, s24
	s_cselect_b32 s27, s21, s66
	s_cselect_b32 s26, s20, s65
	s_add_i32 s69, 0, 0x14000
	s_add_i32 m0, s36, 0xc000
	v_lshl_add_u64 v[186:187], s[22:23], 0, v[130:131]
	global_load_lds_dwordx4 v[186:187], off
	s_add_i32 m0, s36, 0xe000
	v_lshl_add_u64 v[186:187], s[22:23], 0, v[132:133]
	global_load_lds_dwordx4 v[186:187], off
	s_waitcnt vmcnt(8)
	s_waitcnt lgkmcnt(0)
	s_barrier
	s_setprio 1
	s_waitcnt lgkmcnt(0)
	v_mfma_f32_16x16x32_bf16 v[124:127], v[134:137], v[170:173], v[124:127]
	v_mfma_f32_16x16x32_bf16 v[96:99], v[146:149], v[170:173], v[96:99]
	v_mfma_f32_16x16x32_bf16 v[120:123], v[134:137], v[178:181], v[120:123]
	v_mfma_f32_16x16x32_bf16 v[92:95], v[146:149], v[178:181], v[92:95]
	v_mfma_f32_16x16x32_bf16 v[116:119], v[134:137], v[192:195], v[116:119]
	v_mfma_f32_16x16x32_bf16 v[84:87], v[146:149], v[192:195], v[84:87]
	v_mfma_f32_16x16x32_bf16 v[112:115], v[134:137], v[234:237], v[112:115]
	v_mfma_f32_16x16x32_bf16 v[80:83], v[146:149], v[234:237], v[80:83]
	v_mfma_f32_16x16x32_bf16 v[124:127], v[142:145], v[174:177], v[124:127]
	v_mfma_f32_16x16x32_bf16 v[96:99], v[150:153], v[174:177], v[96:99]
	v_mfma_f32_16x16x32_bf16 v[120:123], v[142:145], v[182:185], v[120:123]
	v_mfma_f32_16x16x32_bf16 v[92:95], v[150:153], v[182:185], v[92:95]
	v_mfma_f32_16x16x32_bf16 v[116:119], v[142:145], v[230:233], v[116:119]
	v_mfma_f32_16x16x32_bf16 v[84:87], v[150:153], v[230:233], v[84:87]
	v_mfma_f32_16x16x32_bf16 v[112:115], v[142:145], v[238:241], v[112:115]
	v_mfma_f32_16x16x32_bf16 v[80:83], v[150:153], v[238:241], v[80:83]
	s_setprio 0
	s_setprio 1
	v_mfma_f32_16x16x32_bf16 v[64:67], v[154:157], v[170:173], v[64:67]
	v_mfma_f32_16x16x32_bf16 v[36:39], v[162:165], v[170:173], v[36:39]
	v_mfma_f32_16x16x32_bf16 v[56:59], v[154:157], v[178:181], v[56:59]
	v_mfma_f32_16x16x32_bf16 v[24:27], v[162:165], v[178:181], v[24:27]
	v_mfma_f32_16x16x32_bf16 v[52:55], v[154:157], v[192:195], v[52:55]
	v_mfma_f32_16x16x32_bf16 v[20:23], v[162:165], v[192:195], v[20:23]
	v_mfma_f32_16x16x32_bf16 v[48:51], v[154:157], v[234:237], v[48:51]
	v_mfma_f32_16x16x32_bf16 v[16:19], v[162:165], v[234:237], v[16:19]
	v_mfma_f32_16x16x32_bf16 v[64:67], v[158:161], v[174:177], v[64:67]
	v_mfma_f32_16x16x32_bf16 v[36:39], v[166:169], v[174:177], v[36:39]
	v_mfma_f32_16x16x32_bf16 v[56:59], v[158:161], v[182:185], v[56:59]
	v_mfma_f32_16x16x32_bf16 v[24:27], v[166:169], v[182:185], v[24:27]
	v_mfma_f32_16x16x32_bf16 v[52:55], v[158:161], v[230:233], v[52:55]
	v_mfma_f32_16x16x32_bf16 v[20:23], v[166:169], v[230:233], v[20:23]
	v_mfma_f32_16x16x32_bf16 v[48:51], v[158:161], v[238:241], v[48:51]
	v_mfma_f32_16x16x32_bf16 v[16:19], v[166:169], v[238:241], v[16:19]
	s_setprio 0
	s_barrier
	ds_read_b128 v[170:173], v141 offset:16384
	ds_read_b128 v[174:177], v141 offset:17408
	ds_read_b128 v[178:181], v141 offset:18432
	ds_read_b128 v[182:185], v141 offset:19456
	ds_read_b128 v[192:195], v141 offset:20480
	ds_read_b128 v[230:233], v141 offset:21504
	ds_read_b128 v[234:237], v141 offset:22528
	ds_read_b128 v[238:241], v141 offset:23552
	s_add_i32 s22, s68, s35
	s_mov_b32 m0, s22
	v_lshl_add_u64 v[186:187], s[26:27], 0, v[188:189]
	global_load_lds_dwordx4 v[186:187], off
	s_add_i32 m0, s22, 0x2000
	s_add_u32 s22, s26, 0xb0000
	v_lshl_add_u64 v[196:197], s[26:27], 0, v[128:129]
	s_addc_u32 s23, s27, 0
	s_add_i32 s68, s69, s35
	global_load_lds_dwordx4 v[196:197], off
	v_lshl_add_u64 v[242:243], s[22:23], 0, v[188:189]
	s_mov_b32 m0, s68
	v_lshl_add_u64 v[244:245], s[28:29], 0, v[128:129]
	global_load_lds_dwordx4 v[242:243], off
	s_add_i32 m0, s68, 0x2000
	v_lshl_add_u64 v[242:243], s[22:23], 0, v[128:129]
	global_load_lds_dwordx4 v[242:243], off
	s_mov_b32 m0, s36
	v_lshl_add_u64 v[242:243], s[28:29], 0, v[188:189]
	global_load_lds_dwordx4 v[242:243], off
	s_mov_b32 m0, s37
	s_nop 0
	global_load_lds_dwordx4 v[244:245], off
	s_waitcnt vmcnt(8)
	s_waitcnt lgkmcnt(0)
	s_barrier
; #define PG8_STAGE(bufoff, gbase, voff) do { _Pragma("unroll") for (int _i = 0; _i < 2; ++_i) \
;         __builtin_amdgcn_global_load_lds((const unsigned*)((const char*)(gbase) + (voff)[_i]), (PG8_LAS unsigned*)(lds + (bufoff) + ldsw + _i * 8192), 16, 0, 0); } while (0)
; #define PG8_LDA(dst, b, h) do { _Pragma("unroll") for (int m = 0; m < 4; ++m) _Pragma("unroll") for (int k = 0; k < 2; ++k) dst[m][k] = *(const PG8_LAS bf16x8*)(lds + PG8_SA(b, h) + aoff + m * 2048 + k * 1024); } while (0)
; #define PG8_LDB(dst, b, h) do { _Pragma("unroll") for (int n = 0; n < 2; ++n) _Pragma("unroll") for (int k = 0; k < 2; ++k) dst[n][k] = *(const PG8_LAS bf16x8*)(lds + PG8_SB(b, h) + boff + n * 2048 + k * 1024); } while (0)
; #define PG8_MMA(ai, bj, At, Bt) do { __builtin_amdgcn_s_setprio(1); _Pragma("unroll") for (int m = 0; m < 4; ++m) _Pragma("unroll") for (int n = 0; n < 2; ++n) _Pragma("unroll") for (int k = 0; k < 2; ++k) \
;         acc[ai][bj][m][n] = __builtin_amdgcn_mfma_f32_16x16x32_bf16(Bt[n][k], At[m][k], acc[ai][bj][m][n], 0, 0, 0); __builtin_amdgcn_s_setprio(0); } while (0)
; #define PG8_WAIT_V(n) asm volatile("s_waitcnt vmcnt(" #n ")" ::: "memory")
; #define PG8_WAIT_L(n) asm volatile("s_waitcnt lgkmcnt(" #n ")" ::: "memory")
; #define PG8_BAR __builtin_amdgcn_s_barrier()
; #define PG8_SCHED __builtin_amdgcn_sched_barrier(0)
; template <class Epi, class Sched, bool ALIGN_EPI = false, bool SP2 = false>
; __device__ __forceinline__ void gemm_phase(PG8_LAS unsigned char* lds, const Gemm g, const Sched& S, const Epi& E) {
;     ...
;             PG8_WAIT_V(8); PG8_WAIT_L(0); PG8_BAR; PG8_MMA(1, 0, At, B0); PG8_MMA(1, 1, At, B1); PG8_BAR; PG8_SCHED;
;             PG8_LDB(B0, 1, 0); PG8_LDB(B1, 1, 1); PG8_SCHED; PG8_LDA(At, 1, 0); PG8_STAGE(PG8_SA(0, 1), a2 + hstepA, voffA);
;             PG8_WAIT_V(8); PG8_WAIT_L(0); PG8_BAR; PG8_MMA(0, 0, At, B0); PG8_MMA(0, 1, At, B1); PG8_BAR; PG8_SCHED;
	s_setprio 1
	s_waitcnt lgkmcnt(0)
	v_mfma_f32_16x16x32_bf16 v[108:111], v[134:137], v[170:173], v[108:111]
	v_mfma_f32_16x16x32_bf16 v[76:79], v[146:149], v[170:173], v[76:79]
	v_mfma_f32_16x16x32_bf16 v[104:107], v[134:137], v[178:181], v[104:107]
	v_mfma_f32_16x16x32_bf16 v[72:75], v[146:149], v[178:181], v[72:75]
	v_mfma_f32_16x16x32_bf16 v[100:103], v[134:137], v[192:195], v[100:103]
	v_mfma_f32_16x16x32_bf16 v[68:71], v[146:149], v[192:195], v[68:71]
	v_mfma_f32_16x16x32_bf16 v[88:91], v[134:137], v[234:237], v[88:91]
	v_mfma_f32_16x16x32_bf16 v[60:63], v[146:149], v[234:237], v[60:63]
	v_mfma_f32_16x16x32_bf16 v[108:111], v[142:145], v[174:177], v[108:111]
	v_mfma_f32_16x16x32_bf16 v[76:79], v[150:153], v[174:177], v[76:79]
	v_mfma_f32_16x16x32_bf16 v[104:107], v[142:145], v[182:185], v[104:107]
	v_mfma_f32_16x16x32_bf16 v[72:75], v[150:153], v[182:185], v[72:75]
	v_mfma_f32_16x16x32_bf16 v[100:103], v[142:145], v[230:233], v[100:103]
	v_mfma_f32_16x16x32_bf16 v[68:71], v[150:153], v[230:233], v[68:71]
	v_mfma_f32_16x16x32_bf16 v[88:91], v[142:145], v[238:241], v[88:91]
	v_mfma_f32_16x16x32_bf16 v[60:63], v[150:153], v[238:241], v[60:63]
	s_setprio 0
	s_setprio 1
	v_mfma_f32_16x16x32_bf16 v[44:47], v[154:157], v[170:173], v[44:47]
	v_mfma_f32_16x16x32_bf16 v[12:15], v[162:165], v[170:173], v[12:15]
	v_mfma_f32_16x16x32_bf16 v[40:43], v[154:157], v[178:181], v[40:43]
	v_mfma_f32_16x16x32_bf16 v[8:11], v[162:165], v[178:181], v[8:11]
	v_mfma_f32_16x16x32_bf16 v[32:35], v[154:157], v[192:195], v[32:35]
	v_mfma_f32_16x16x32_bf16 v[4:7], v[162:165], v[192:195], v[4:7]
	v_mfma_f32_16x16x32_bf16 v[28:31], v[154:157], v[234:237], v[28:31]
	v_mfma_f32_16x16x32_bf16 v[0:3], v[162:165], v[234:237], v[0:3]
	v_mfma_f32_16x16x32_bf16 v[44:47], v[158:161], v[174:177], v[44:47]
	v_mfma_f32_16x16x32_bf16 v[12:15], v[166:169], v[174:177], v[12:15]
	v_mfma_f32_16x16x32_bf16 v[40:43], v[158:161], v[182:185], v[40:43]
	v_mfma_f32_16x16x32_bf16 v[8:11], v[166:169], v[182:185], v[8:11]
	v_mfma_f32_16x16x32_bf16 v[32:35], v[158:161], v[230:233], v[32:35]
	v_mfma_f32_16x16x32_bf16 v[4:7], v[166:169], v[230:233], v[4:7]
	v_mfma_f32_16x16x32_bf16 v[28:31], v[158:161], v[238:241], v[28:31]
	v_mfma_f32_16x16x32_bf16 v[0:3], v[166:169], v[238:241], v[0:3]
	s_setprio 0
	s_barrier
	v_add_u32_e32 v150, 0x18000, v140
	v_add_u32_e32 v166, 0x1c000, v140
	ds_read_b128 v[134:137], v150
	ds_read_b128 v[142:145], v150 offset:1024
	ds_read_b128 v[146:149], v150 offset:2048
	ds_read_b128 v[150:153], v150 offset:3072
	ds_read_b128 v[154:157], v166
	ds_read_b128 v[158:161], v166 offset:1024
	ds_read_b128 v[162:165], v166 offset:2048
	ds_read_b128 v[166:169], v166 offset:3072
	ds_read_b128 v[170:173], v141 offset:32768
	ds_read_b128 v[174:177], v141 offset:33792
	ds_read_b128 v[178:181], v141 offset:34816
	ds_read_b128 v[182:185], v141 offset:35840
	ds_read_b128 v[192:195], v141 offset:36864
	ds_read_b128 v[230:233], v141 offset:37888
	ds_read_b128 v[234:237], v141 offset:38912
	ds_read_b128 v[238:241], v141 offset:39936
	s_add_i32 s68, 0, 0x18000
	s_add_i32 s69, 0, 0x1c000
	s_add_u32 s22, s28, 0xb0000
	s_addc_u32 s23, s29, 0
	s_mov_b32 m0, s44
	v_lshl_add_u64 v[246:247], s[22:23], 0, v[188:189]
	global_load_lds_dwordx4 v[246:247], off
	s_mov_b32 m0, s45
	v_lshl_add_u64 v[246:247], s[22:23], 0, v[128:129]
	global_load_lds_dwordx4 v[246:247], off
	s_waitcnt vmcnt(8)
	s_waitcnt lgkmcnt(0)
	s_barrier
	s_setprio 1
	s_waitcnt lgkmcnt(0)
	v_mfma_f32_16x16x32_bf16 v[124:127], v[134:137], v[170:173], v[124:127]
	v_mfma_f32_16x16x32_bf16 v[96:99], v[146:149], v[170:173], v[96:99]
	v_mfma_f32_16x16x32_bf16 v[120:123], v[134:137], v[178:181], v[120:123]
	v_mfma_f32_16x16x32_bf16 v[92:95], v[146:149], v[178:181], v[92:95]
	v_mfma_f32_16x16x32_bf16 v[116:119], v[134:137], v[192:195], v[116:119]
	v_mfma_f32_16x16x32_bf16 v[84:87], v[146:149], v[192:195], v[84:87]
	v_mfma_f32_16x16x32_bf16 v[112:115], v[134:137], v[234:237], v[112:115]
	v_mfma_f32_16x16x32_bf16 v[80:83], v[146:149], v[234:237], v[80:83]
	v_mfma_f32_16x16x32_bf16 v[124:127], v[142:145], v[174:177], v[124:127]
	v_mfma_f32_16x16x32_bf16 v[96:99], v[150:153], v[174:177], v[96:99]
	v_mfma_f32_16x16x32_bf16 v[120:123], v[142:145], v[182:185], v[120:123]
	v_mfma_f32_16x16x32_bf16 v[92:95], v[150:153], v[182:185], v[92:95]
	v_mfma_f32_16x16x32_bf16 v[116:119], v[142:145], v[230:233], v[116:119]
	v_mfma_f32_16x16x32_bf16 v[84:87], v[150:153], v[230:233], v[84:87]
	v_mfma_f32_16x16x32_bf16 v[112:115], v[142:145], v[238:241], v[112:115]
	v_mfma_f32_16x16x32_bf16 v[80:83], v[150:153], v[238:241], v[80:83]
	s_setprio 0
	s_setprio 1
	v_mfma_f32_16x16x32_bf16 v[64:67], v[154:157], v[170:173], v[64:67]
	v_mfma_f32_16x16x32_bf16 v[36:39], v[162:165], v[170:173], v[36:39]
	v_mfma_f32_16x16x32_bf16 v[56:59], v[154:157], v[178:181], v[56:59]
	v_mfma_f32_16x16x32_bf16 v[24:27], v[162:165], v[178:181], v[24:27]
	v_mfma_f32_16x16x32_bf16 v[52:55], v[154:157], v[192:195], v[52:55]
	v_mfma_f32_16x16x32_bf16 v[20:23], v[162:165], v[192:195], v[20:23]
	v_mfma_f32_16x16x32_bf16 v[48:51], v[154:157], v[234:237], v[48:51]
	v_mfma_f32_16x16x32_bf16 v[16:19], v[162:165], v[234:237], v[16:19]
	v_mfma_f32_16x16x32_bf16 v[64:67], v[158:161], v[174:177], v[64:67]
	v_mfma_f32_16x16x32_bf16 v[36:39], v[166:169], v[174:177], v[36:39]
	v_mfma_f32_16x16x32_bf16 v[56:59], v[158:161], v[182:185], v[56:59]
	v_mfma_f32_16x16x32_bf16 v[24:27], v[166:169], v[182:185], v[24:27]
	v_mfma_f32_16x16x32_bf16 v[52:55], v[158:161], v[230:233], v[52:55]
	v_mfma_f32_16x16x32_bf16 v[20:23], v[166:169], v[230:233], v[20:23]
	v_mfma_f32_16x16x32_bf16 v[48:51], v[158:161], v[238:241], v[48:51]
	v_mfma_f32_16x16x32_bf16 v[16:19], v[166:169], v[238:241], v[16:19]
	s_setprio 0
	s_barrier
; #define PG8_STAGE(bufoff, gbase, voff) do { _Pragma("unroll") for (int _i = 0; _i < 2; ++_i) \
;         __builtin_amdgcn_global_load_lds((const unsigned*)((const char*)(gbase) + (voff)[_i]), (PG8_LAS unsigned*)(lds + (bufoff) + ldsw + _i * 8192), 16, 0, 0); } while (0)
; #define PG8_LDA(dst, b, h) do { _Pragma("unroll") for (int m = 0; m < 4; ++m) _Pragma("unroll") for (int k = 0; k < 2; ++k) dst[m][k] = *(const PG8_LAS bf16x8*)(lds + PG8_SA(b, h) + aoff + m * 2048 + k * 1024); } while (0)
; #define PG8_MMA(ai, bj, At, Bt) do { __builtin_amdgcn_s_setprio(1); _Pragma("unroll") for (int m = 0; m < 4; ++m) _Pragma("unroll") for (int n = 0; n < 2; ++n) _Pragma("unroll") for (int k = 0; k < 2; ++k) \
;         acc[ai][bj][m][n] = __builtin_amdgcn_mfma_f32_16x16x32_bf16(Bt[n][k], At[m][k], acc[ai][bj][m][n], 0, 0, 0); __builtin_amdgcn_s_setprio(0); } while (0)
; #define PG8_WAIT_V(n) asm volatile("s_waitcnt vmcnt(" #n ")" ::: "memory")
; #define PG8_WAIT_L(n) asm volatile("s_waitcnt lgkmcnt(" #n ")" ::: "memory")
; #define PG8_BAR __builtin_amdgcn_s_barrier()
; #define PG8_SCHED __builtin_amdgcn_sched_barrier(0)
; template <class Epi, class Sched, bool ALIGN_EPI = false, bool SP2 = false>
; __device__ __forceinline__ void gemm_phase(PG8_LAS unsigned char* lds, const Gemm g, const Sched& S, const Epi& E) {
;     ...
;             PG8_LDA(At, 1, 1); PG8_STAGE(PG8_SB(1, 0), b3, voffB); PG8_STAGE(PG8_SB(1, 1), b3 + hstepB, voffB); PG8_STAGE(PG8_SA(1, 0), a3, voffA);
;             PG8_WAIT_V(8); PG8_WAIT_L(0); PG8_BAR; PG8_MMA(1, 0, At, B0); PG8_MMA(1, 1, At, B1); PG8_BAR; PG8_SCHED;
	ds_read_b128 v[170:173], v141 offset:49152
	ds_read_b128 v[174:177], v141 offset:50176
	ds_read_b128 v[178:181], v141 offset:51200
	ds_read_b128 v[182:185], v141 offset:52224
	ds_read_b128 v[192:195], v141 offset:53248
	ds_read_b128 v[230:233], v141 offset:54272
	ds_read_b128 v[234:237], v141 offset:55296
	ds_read_b128 v[238:241], v141 offset:56320
	s_add_i32 s22, s68, s35
	s_mov_b32 m0, s22
	v_lshl_add_u64 v[186:187], v[186:187], 0, s[94:95]
	global_load_lds_dwordx4 v[186:187], off
	s_add_i32 m0, s22, 0x2000
	s_add_u32 s22, s26, 0xb0080
	v_lshl_add_u64 v[186:187], v[196:197], 0, s[94:95]
	s_addc_u32 s23, s27, 0
	s_add_i32 s26, s69, s35
	global_load_lds_dwordx4 v[186:187], off
	s_mov_b32 m0, s26
	v_lshl_add_u64 v[186:187], s[22:23], 0, v[188:189]
	global_load_lds_dwordx4 v[186:187], off
	s_add_i32 m0, s26, 0x2000
	v_lshl_add_u64 v[186:187], s[22:23], 0, v[128:129]
	global_load_lds_dwordx4 v[186:187], off
	s_mov_b32 m0, s57
	v_lshl_add_u64 v[186:187], v[242:243], 0, s[94:95]
	global_load_lds_dwordx4 v[186:187], off
	s_mov_b32 m0, s58
	v_lshl_add_u64 v[186:187], v[244:245], 0, s[94:95]
	global_load_lds_dwordx4 v[186:187], off
	s_waitcnt vmcnt(8)
	s_waitcnt lgkmcnt(0)
	s_barrier
	s_setprio 1
	s_waitcnt lgkmcnt(0)
	v_mfma_f32_16x16x32_bf16 v[108:111], v[134:137], v[170:173], v[108:111]
	v_mfma_f32_16x16x32_bf16 v[76:79], v[146:149], v[170:173], v[76:79]
	v_mfma_f32_16x16x32_bf16 v[104:107], v[134:137], v[178:181], v[104:107]
	v_mfma_f32_16x16x32_bf16 v[72:75], v[146:149], v[178:181], v[72:75]
	v_mfma_f32_16x16x32_bf16 v[100:103], v[134:137], v[192:195], v[100:103]
	v_mfma_f32_16x16x32_bf16 v[68:71], v[146:149], v[192:195], v[68:71]
	v_mfma_f32_16x16x32_bf16 v[88:91], v[134:137], v[234:237], v[88:91]
	v_mfma_f32_16x16x32_bf16 v[60:63], v[146:149], v[234:237], v[60:63]
	v_mfma_f32_16x16x32_bf16 v[108:111], v[142:145], v[174:177], v[108:111]
	v_mfma_f32_16x16x32_bf16 v[76:79], v[150:153], v[174:177], v[76:79]
	v_mfma_f32_16x16x32_bf16 v[104:107], v[142:145], v[182:185], v[104:107]
	v_mfma_f32_16x16x32_bf16 v[72:75], v[150:153], v[182:185], v[72:75]
	v_mfma_f32_16x16x32_bf16 v[100:103], v[142:145], v[230:233], v[100:103]
	v_mfma_f32_16x16x32_bf16 v[68:71], v[150:153], v[230:233], v[68:71]
	v_mfma_f32_16x16x32_bf16 v[88:91], v[142:145], v[238:241], v[88:91]
	v_mfma_f32_16x16x32_bf16 v[60:63], v[150:153], v[238:241], v[60:63]
	s_setprio 0
	s_setprio 1
	v_mfma_f32_16x16x32_bf16 v[44:47], v[154:157], v[170:173], v[44:47]
	v_mfma_f32_16x16x32_bf16 v[12:15], v[162:165], v[170:173], v[12:15]
	v_mfma_f32_16x16x32_bf16 v[40:43], v[154:157], v[178:181], v[40:43]
	v_mfma_f32_16x16x32_bf16 v[8:11], v[162:165], v[178:181], v[8:11]
	v_mfma_f32_16x16x32_bf16 v[32:35], v[154:157], v[192:195], v[32:35]
	v_mfma_f32_16x16x32_bf16 v[4:7], v[162:165], v[192:195], v[4:7]
	v_mfma_f32_16x16x32_bf16 v[28:31], v[154:157], v[234:237], v[28:31]
	v_mfma_f32_16x16x32_bf16 v[0:3], v[162:165], v[234:237], v[0:3]
	v_mfma_f32_16x16x32_bf16 v[44:47], v[158:161], v[174:177], v[44:47]
	v_mfma_f32_16x16x32_bf16 v[12:15], v[166:169], v[174:177], v[12:15]
	v_mfma_f32_16x16x32_bf16 v[40:43], v[158:161], v[182:185], v[40:43]
	v_mfma_f32_16x16x32_bf16 v[8:11], v[166:169], v[182:185], v[8:11]
	v_mfma_f32_16x16x32_bf16 v[32:35], v[158:161], v[230:233], v[32:35]
	v_mfma_f32_16x16x32_bf16 v[4:7], v[166:169], v[230:233], v[4:7]
	v_mfma_f32_16x16x32_bf16 v[28:31], v[158:161], v[238:241], v[28:31]
	v_mfma_f32_16x16x32_bf16 v[0:3], v[166:169], v[238:241], v[0:3]
	s_setprio 0
	s_barrier
	s_add_i32 s67, s67, 2
	s_add_u32 s65, s65, 0x100
	s_addc_u32 s66, s66, 0
	s_cmp_gt_u32 s67, 41
	s_mov_b64 s[22:23], s[24:25]
	s_cbranch_scc0 .LBB0_1993
	s_and_b64 vcc, exec, s[14:15]
	s_cbranch_vccz .LBB0_1996
	s_barrier
